# MLA loop halves list-scheduled with K-frag double buffering, conflict-free K swizzle (row&15), dilated unit loads issued in one batch
# speedup vs baseline: 1.0127x; 1.0127x over previous
; DI int v_st64(int k, int c) { const int kk = (k & ~0xC) | ((k & 4) << 1) | ((k & 8) >> 1); return ((kk >> 3) * 2 + (c >> 5)) * 512 + ((kk & 7) * 32 + (c & 31)) * 2; }
; DI void unit(const bf16* __restrict__ QKV, const int* __restrict__ pos, bf16* __restrict__ OA, float* __restrict__ LSE,
;              int b, int h, int d, int r, int qb, float slope, char* lds) {
;     ...
;   auto stage = [&](const int i0) {
;     bf16x8 kreg[3], vreg[3];
; #pragma unroll
;     for (int i = 0; i < 3; ++i) { const int idx = tid + (i0 + i) * 512, row = idx >> 3, ch = idx & 7, v = u0 - 64 + row; const bool ok = (v >= 0) && (v < L);
;       const unsigned go = (unsigned)((r + d * (ok ? v : 0)) * 64 + ch * 8) * 2u;
;       kreg[i] = *(const bf16x8*)((const char*)base + PLANE + go); vreg[i] = *(const bf16x8*)((const char*)base + 2 * PLANE + go);
;       if (!ok) { kreg[i] = bf16x8{}; vreg[i] = bf16x8{}; } }
; #pragma unroll
;     for (int i = 0; i < 3; ++i) { const int idx = tid + (i0 + i) * 512, row = idx >> 3, ch = idx & 7;
;       *(bf16x8*)(K_lds + PSWZ(row, ch * 16)) = kreg[i]; *(bf16x8*)(V_lds + v_st64(row, ch * 8)) = vreg[i]; }
; __global__ void __launch_bounds__(512, 2) fwd_megakernel(Params P) {
;     ...
;         if (PH(18)) for (int u = bid; u < 3072; u += G) {
;             const int br = u >> 10, v = u & 1023, h = v & 7, w = v >> 3;
;             const int b = w >> 4, blk = w & 15;
;             int d, r, qb; if (br == 0) { d = 1; r = 0; qb = blk; } else if (br == 1) { d = 4; r = blk & 3; qb = blk >> 2; } else { d = 16; r = blk; qb = 0; }
;             const float slope = __builtin_exp2f(-(float)(h + 1));
;             dil::unit(QKV, P.pos, OA + (size_t)br * T * 512, LSE + (size_t)br * T * 8, b, h, d, r, qb, slope, (char*)lds);
.LBB0_855:
	s_cmpk_gt_i32 s33, 0xbff
	s_cbranch_scc1 .LBB0_872
	s_add_u32 s0, s68, 0x9c00000
	s_addc_u32 s1, s69, 0
	s_add_u32 s10, s68, 0xfc00000
	s_addc_u32 s11, s69, 0
	s_add_u32 s13, s68, 0x7400000
	s_addc_u32 s38, s69, 0
	s_mov_b32 s9, 0
	s_movk_i32 s39, 0x70
	s_movk_i32 s42, 0x180
	v_mov_b32_e32 v93, 0
	s_mov_b32 s43, 0x42fc0000
	s_movk_i32 s44, 0x60
	s_mov_b32 s45, 0xf149f2ca
	v_mov_b32_e32 v96, 0x42800000
	s_add_i32 s46, 0, 0x18000
	v_mov_b32_e32 v97, 0xf149f2ca
	v_lshrrev_b32_e32 v234, 3, v242
	v_lshlrev_b32_e32 v235, 4, v242
	v_and_b32_e32 v235, 0x70, v235
	v_lshrrev_b32_e32 v222, 1, v234
	v_and_b32_e32 v222, 7, v222
	v_lshlrev_b32_e32 v222, 4, v222
	v_xor_b32_e32 v222, v222, v235
	v_lshl_or_b32 v222, v234, 7, v222
	v_and_b32_e32 v223, 51, v234
	v_and_b32_e32 v224, 4, v234
	v_lshlrev_b32_e32 v224, 1, v224
	v_or_b32_e32 v223, v223, v224
	v_and_b32_e32 v224, 8, v234
	v_lshrrev_b32_e32 v224, 1, v224
	v_or_b32_e32 v223, v223, v224
	v_lshrrev_b32_e32 v224, 3, v223
	v_lshlrev_b32_e32 v224, 1, v224
	v_bfe_u32 v225, v242, 2, 1
	v_add_u32_e32 v224, v224, v225
	v_lshlrev_b32_e32 v224, 9, v224
	v_and_b32_e32 v225, 7, v223
	v_lshlrev_b32_e32 v225, 5, v225
	v_and_b32_e32 v226, 3, v242
	v_lshl_or_b32 v225, v226, 3, v225
	v_lshlrev_b32_e32 v225, 1, v225
	v_add_u32_e32 v223, v224, v225
	v_add_u32_e32 v223, 0xc000, v223
	s_mov_b32 s47, s33
	s_branch .LBB0_858

; #define SBAR() __builtin_amdgcn_sched_barrier(0)
; DI int v_st64(int k, int c) { const int kk = (k & ~0xC) | ((k & 4) << 1) | ((k & 8) >> 1); return ((kk >> 3) * 2 + (c >> 5)) * 512 + ((kk & 7) * 32 + (c & 31)) * 2; }
; DI void unit(const bf16* __restrict__ QKV, const int* __restrict__ pos, bf16* __restrict__ OA, float* __restrict__ LSE,
;              int b, int h, int d, int r, int qb, float slope, char* lds) {
;     ...
;   auto stage = [&](const int i0) {
;     bf16x8 kreg[3], vreg[3];
; #pragma unroll
;     for (int i = 0; i < 3; ++i) { const int idx = tid + (i0 + i) * 512, row = idx >> 3, ch = idx & 7, v = u0 - 64 + row; const bool ok = (v >= 0) && (v < L);
;       const unsigned go = (unsigned)((r + d * (ok ? v : 0)) * 64 + ch * 8) * 2u;
;       kreg[i] = *(const bf16x8*)((const char*)base + PLANE + go); vreg[i] = *(const bf16x8*)((const char*)base + 2 * PLANE + go);
;       if (!ok) { kreg[i] = bf16x8{}; vreg[i] = bf16x8{}; } }
; #pragma unroll
;     for (int i = 0; i < 3; ++i) { const int idx = tid + (i0 + i) * 512, row = idx >> 3, ch = idx & 7;
;       *(bf16x8*)(K_lds + PSWZ(row, ch * 16)) = kreg[i]; *(bf16x8*)(V_lds + v_st64(row, ch * 8)) = vreg[i]; }
;   };
;   stage(0); SBAR(); stage(3); SBAR();
;   float pkv = 3.0e8f; if (tid < 384) { const int v = u0 - 64 + tid; if (v >= 0 && v < L) pkv = (float)pos[b * SEQ + r + d * v]; }
;   const int uq = u0 + wid * 32 + r32, tq = r + d * uq;
;   bf16x8 qr[4];
; #pragma unroll
;   for (int d0 = 0; d0 < 4; ++d0) qr[d0] = *(const bf16x8*)((const char*)base + (unsigned)(tq * 64 + d0 * 16 + hi * 8) * 2u);
;   const int pq = pos[b * SEQ + tq];
;   if (tid < 384) ((float*)posk)[tid] = pkv;
.LBB0_864:
	s_and_b32 s48, s47, 7
	s_bfe_u32 s30, s47, 0x30007
	s_ff1_i32_b32 s3, s8
	s_lshr_b32 s49, 0x1000, s3
	s_lshl_b32 s31, s2, 8
	s_lshl_b32 s2, s48, 19
	s_lshl_b32 s3, s30, 22
	s_or_b32 s2, s3, s2
	s_add_u32 s16, s10, s2
	v_mov_b32_e32 v4, v242
	s_addc_u32 s17, s11, 0
	s_sub_i32 s50, s31, 64
	s_add_u32 s18, s16, 0x2000000
	s_addc_u32 s19, s17, 0
	s_add_u32 s20, s16, 0x4000000
	s_addc_u32 s21, s17, 0
	s_lshl_b32 s94, s30, 12
	s_or_b32 s94, s15, s94
	v_ashrrev_i32_e32 v6, 6, v4
	v_lshlrev_b32_e32 v102, 5, v6
	v_and_b32_e32 v100, 31, v4
	v_add_u32_e32 v0, s31, v102
	v_or_b32_e32 v0, v0, v100
	v_bfe_u32 v101, v4, 5, 1
	v_mul_lo_u32 v0, v0, s8
	v_add_u32_e32 v7, s15, v0
	v_lshlrev_b32_e32 v92, 4, v101
	v_lshl_or_b32 v8, v7, 7, v92
	v_lshl_add_u32 v94, s30, 12, v7
	global_load_dwordx4 v[0:3], v8, s[16:17]
	global_load_dwordx4 v[88:91], v8, s[16:17] offset:32
	global_load_dwordx4 v[84:87], v8, s[16:17] offset:64
	global_load_dwordx4 v[80:83], v8, s[16:17] offset:96
	v_ashrrev_i32_e32 v95, 31, v94
	v_lshl_add_u64 v[8:9], v[94:95], 2, s[40:41]
	global_load_dword v103, v[8:9], off
	v_add_u32_e32 v214, s50, v234
	s_add_i32 s95, s50, 64
	v_add_u32_e32 v215, s95, v234
	s_add_i32 s95, s50, 128
	v_add_u32_e32 v216, s95, v234
	s_add_i32 s95, s50, 192
	v_add_u32_e32 v217, s95, v234
	s_add_i32 s95, s50, 256
	v_add_u32_e32 v218, s95, v234
	s_add_i32 s95, s50, 320
	v_add_u32_e32 v219, s95, v234
	v_add_u32_e32 v220, s50, v4
	v_cmp_gt_u32_e64 s[80:81], s49, v214
	v_cmp_gt_u32_e64 s[82:83], s49, v215
	v_cmp_gt_u32_e64 s[84:85], s49, v216
	v_cmp_gt_u32_e64 s[86:87], s49, v217
	v_cmp_gt_u32_e64 s[88:89], s49, v218
	v_cmp_gt_u32_e64 s[90:91], s49, v219
	v_cmp_gt_u32_e64 s[92:93], s49, v220
	v_cmp_gt_i32_e32 vcc, s42, v4
	v_cndmask_b32_e64 v214, 0, v214, s[80:81]
	v_cndmask_b32_e64 v215, 0, v215, s[82:83]
	v_cndmask_b32_e64 v216, 0, v216, s[84:85]
	v_cndmask_b32_e64 v217, 0, v217, s[86:87]
	v_cndmask_b32_e64 v218, 0, v218, s[88:89]
	v_cndmask_b32_e64 v219, 0, v219, s[90:91]
	s_and_b64 s[92:93], s[92:93], vcc
	v_mul_lo_u32 v214, v214, s8
	v_mul_lo_u32 v215, v215, s8
	v_mul_lo_u32 v216, v216, s8
	v_mul_lo_u32 v217, v217, s8
	v_mul_lo_u32 v218, v218, s8
	v_mul_lo_u32 v219, v219, s8
	v_cndmask_b32_e64 v220, 0, v220, s[92:93]
	v_add_u32_e32 v214, s15, v214
	v_add_u32_e32 v215, s15, v215
	v_add_u32_e32 v216, s15, v216
	v_add_u32_e32 v217, s15, v217
	v_add_u32_e32 v218, s15, v218
	v_add_u32_e32 v219, s15, v219
	v_mul_lo_u32 v220, v220, s8
	v_lshl_or_b32 v214, v214, 7, v235
	v_lshl_or_b32 v215, v215, 7, v235
	v_lshl_or_b32 v216, v216, 7, v235
	v_lshl_or_b32 v217, v217, 7, v235
	v_lshl_or_b32 v218, v218, 7, v235
	v_lshl_or_b32 v219, v219, 7, v235
	v_add_lshl_u32 v220, v220, s94, 2
	global_load_dwordx4 v[164:167], v214, s[18:19]
	global_load_dwordx4 v[168:171], v214, s[20:21]
	global_load_dwordx4 v[172:175], v215, s[18:19]
	global_load_dwordx4 v[176:179], v215, s[20:21]
	global_load_dwordx4 v[180:183], v216, s[18:19]
	global_load_dwordx4 v[184:187], v216, s[20:21]
	global_load_dwordx4 v[188:191], v217, s[18:19]
	global_load_dwordx4 v[192:195], v217, s[20:21]
	global_load_dwordx4 v[196:199], v218, s[18:19]
	global_load_dwordx4 v[200:203], v218, s[20:21]
	global_load_dwordx4 v[204:207], v219, s[18:19]
	global_load_dwordx4 v[208:211], v219, s[20:21]
	global_load_dword v213, v220, s[40:41]
	s_waitcnt vmcnt(11)
	v_cndmask_b32_e64 v164, 0, v164, s[80:81]
	v_cndmask_b32_e64 v165, 0, v165, s[80:81]
	v_cndmask_b32_e64 v166, 0, v166, s[80:81]
	v_cndmask_b32_e64 v167, 0, v167, s[80:81]
	v_cndmask_b32_e64 v168, 0, v168, s[80:81]
	v_cndmask_b32_e64 v169, 0, v169, s[80:81]
	v_cndmask_b32_e64 v170, 0, v170, s[80:81]
	v_cndmask_b32_e64 v171, 0, v171, s[80:81]
	ds_write_b128 v222, v[164:167]
	ds_write_b128 v223, v[168:171]
	s_waitcnt vmcnt(9)
	v_cndmask_b32_e64 v172, 0, v172, s[82:83]
	v_cndmask_b32_e64 v173, 0, v173, s[82:83]
	v_cndmask_b32_e64 v174, 0, v174, s[82:83]
	v_cndmask_b32_e64 v175, 0, v175, s[82:83]
	v_cndmask_b32_e64 v176, 0, v176, s[82:83]
	v_cndmask_b32_e64 v177, 0, v177, s[82:83]
	v_cndmask_b32_e64 v178, 0, v178, s[82:83]
	v_cndmask_b32_e64 v179, 0, v179, s[82:83]
	ds_write_b128 v222, v[172:175] offset:8192
	ds_write_b128 v223, v[176:179] offset:8192
	s_waitcnt vmcnt(7)
	v_cndmask_b32_e64 v180, 0, v180, s[84:85]
	v_cndmask_b32_e64 v181, 0, v181, s[84:85]
	v_cndmask_b32_e64 v182, 0, v182, s[84:85]
	v_cndmask_b32_e64 v183, 0, v183, s[84:85]
	v_cndmask_b32_e64 v184, 0, v184, s[84:85]
	v_cndmask_b32_e64 v185, 0, v185, s[84:85]
	v_cndmask_b32_e64 v186, 0, v186, s[84:85]
	v_cndmask_b32_e64 v187, 0, v187, s[84:85]
	ds_write_b128 v222, v[180:183] offset:16384
	ds_write_b128 v223, v[184:187] offset:16384
	s_waitcnt vmcnt(5)
	v_cndmask_b32_e64 v188, 0, v188, s[86:87]
	v_cndmask_b32_e64 v189, 0, v189, s[86:87]
	v_cndmask_b32_e64 v190, 0, v190, s[86:87]
	v_cndmask_b32_e64 v191, 0, v191, s[86:87]
	v_cndmask_b32_e64 v192, 0, v192, s[86:87]
	v_cndmask_b32_e64 v193, 0, v193, s[86:87]
	v_cndmask_b32_e64 v194, 0, v194, s[86:87]
	v_cndmask_b32_e64 v195, 0, v195, s[86:87]
	ds_write_b128 v222, v[188:191] offset:24576
	ds_write_b128 v223, v[192:195] offset:24576
	s_waitcnt vmcnt(3)
	v_cndmask_b32_e64 v196, 0, v196, s[88:89]
	v_cndmask_b32_e64 v197, 0, v197, s[88:89]
	v_cndmask_b32_e64 v198, 0, v198, s[88:89]
	v_cndmask_b32_e64 v199, 0, v199, s[88:89]
	v_cndmask_b32_e64 v200, 0, v200, s[88:89]
	v_cndmask_b32_e64 v201, 0, v201, s[88:89]
	v_cndmask_b32_e64 v202, 0, v202, s[88:89]
	v_cndmask_b32_e64 v203, 0, v203, s[88:89]
	ds_write_b128 v222, v[196:199] offset:32768
	ds_write_b128 v223, v[200:203] offset:32768
	s_waitcnt vmcnt(1)
	v_cndmask_b32_e64 v204, 0, v204, s[90:91]
	v_cndmask_b32_e64 v205, 0, v205, s[90:91]
	v_cndmask_b32_e64 v206, 0, v206, s[90:91]
	v_cndmask_b32_e64 v207, 0, v207, s[90:91]
	v_cndmask_b32_e64 v208, 0, v208, s[90:91]
	v_cndmask_b32_e64 v209, 0, v209, s[90:91]
	v_cndmask_b32_e64 v210, 0, v210, s[90:91]
	v_cndmask_b32_e64 v211, 0, v211, s[90:91]
	ds_write_b128 v222, v[204:207] offset:40960
	ds_write_b128 v223, v[208:211] offset:40960
	s_waitcnt vmcnt(0)
	v_cmp_gt_i32_e32 vcc, s42, v4
	v_cvt_f32_i32_e32 v213, v213
	v_mov_b32_e32 v5, 0x4d8f0d18
	v_cndmask_b32_e64 v5, v5, v213, s[92:93]
	s_and_saveexec_b64 s[2:3], vcc
	v_lshl_add_u32 v7, v4, 2, 0
	v_add_u32_e32 v7, 0x18000, v7
	ds_write_b32 v7, v5
	s_or_b64 exec, exec, s[2:3]
	v_lshlrev_b32_e32 v5, 3, v4
	v_lshlrev_b32_e32 v99, 12, v6
	v_bitop3_b32 v7, v92, v5, s39 bitop3:0x78
	v_lshl_or_b32 v14, v100, 7, v99
	v_add3_u32 v15, 0, v7, v14
	s_waitcnt lgkmcnt(0)
	s_barrier
; #define SBAR() __builtin_amdgcn_sched_barrier(0)
; DI void unit(const bf16* __restrict__ QKV, const int* __restrict__ pos, bf16* __restrict__ OA, float* __restrict__ LSE,
;              int b, int h, int d, int r, int qb, float slope, char* lds) {
;     ...
;   f32x16 p[5];
; #pragma unroll
;   for (int ta = 0; ta < 5; ++ta) { p[ta] = f32x16{};
; #pragma unroll
;     for (int d0 = 0; d0 < 4; ++d0) { const bf16x8 a = *(const bf16x8*)(K_lds + PSWZ(wid * 32 + ta * 32 + r32, (d0 * 16 + hi * 8) * 2));
;       p[ta] = __builtin_amdgcn_mfma_f32_32x32x16_bf16(a, qr[d0], p[ta], 0, 0, 0); }
;     SBAR(); }
;   const float C = 0.125f * 1.4426950408889634f, sl2 = slope * 1.4426950408889634f;
;   const float* pbase = (const float*)posk + wid * 32 + 4 * hi; const float pqf = (float)pq;
;   float mx = -1e30f;
; #pragma unroll
;   for (int ta = 0; ta < 5; ++ta) {
; #pragma unroll
;     for (int g = 0; g < 4; ++g) { const f32x4 pk4 = *(const f32x4*)(pbase + ta * 32 + 8 * g);
; #pragma unroll
;       for (int j = 0; j < 4; ++j) { const int rr = 4 * g + j, kr = j + 8 * g + 4 * hi;
;         float sc = fmaf(__builtin_fabsf(pqf - pk4[j]), -sl2, p[ta][rr] * C);
;         if (ta == 0) sc = (kr >= r32) ? sc : -1e30f;
;         if (ta == 4) sc = (kr <= r32) ? sc : -1e30f;
;         p[ta][rr] = sc; mx = fmaxf(mx, sc); } }
	ds_read_b128 v[6:9], v15
	v_and_b32_e32 v5, 0x70, v5
	v_bitop3_b32 v10, v92, v5, 32 bitop3:0x36
	v_add3_u32 v104, 0, v10, v14
	ds_read_b128 v[10:13], v104
	s_waitcnt vmcnt(4) lgkmcnt(1)
	v_mfma_f32_32x32x16_bf16 v[64:79], v[6:9], v[0:3], 0
	v_bitop3_b32 v6, v92, v5, 64 bitop3:0x36
	v_add3_u32 v108, 0, v6, v14
	ds_read_b128 v[6:9], v108
	v_bitop3_b32 v5, v92, v5, s44 bitop3:0x36
	v_add3_u32 v109, 0, v5, v14
	s_add_i32 s2, s48, 1
	v_cvt_f32_ubyte0_e32 v16, s2
	s_waitcnt vmcnt(3) lgkmcnt(1)
	v_mfma_f32_32x32x16_bf16 v[64:79], v[10:13], v[88:91], v[64:79]
	ds_read_b128 v[10:13], v109
	v_cmp_lt_f32_e32 vcc, s43, v16
	s_and_b64 s[2:3], vcc, exec
	s_cselect_b32 s2, 0xffffffc0, 0
	v_cndmask_b32_e32 v17, 0, v96, vcc
	v_sub_f32_e32 v5, v17, v16
	v_exp_f32_e32 v5, v5
	s_waitcnt vmcnt(2) lgkmcnt(1)
	v_mfma_f32_32x32x16_bf16 v[64:79], v[6:9], v[84:87], v[64:79]
	s_ashr_i32 s15, s14, 31
	v_and_b32_e32 v98, 63, v4
	v_ldexp_f32 v110, v5, s2
	s_waitcnt vmcnt(1) lgkmcnt(0)
	v_mfma_f32_32x32x16_bf16 v[64:79], v[10:13], v[80:83], v[64:79]
	ds_read_b128 v[4:7], v15 offset:4096
	ds_read_b128 v[8:11], v104 offset:4096
	s_waitcnt lgkmcnt(1)
	v_mfma_f32_32x32x16_bf16 v[48:63], v[4:7], v[0:3], 0
	s_waitcnt lgkmcnt(0)
	v_mfma_f32_32x32x16_bf16 v[48:63], v[8:11], v[88:91], v[48:63]
	ds_read_b128 v[4:7], v108 offset:4096
	ds_read_b128 v[8:11], v109 offset:4096
	s_waitcnt lgkmcnt(1)
	v_mfma_f32_32x32x16_bf16 v[48:63], v[4:7], v[84:87], v[48:63]
	s_waitcnt lgkmcnt(0)
	v_mfma_f32_32x32x16_bf16 v[48:63], v[8:11], v[80:83], v[48:63]
	ds_read_b128 v[4:7], v15 offset:8192
	ds_read_b128 v[8:11], v104 offset:8192
	s_waitcnt lgkmcnt(1)
	v_mfma_f32_32x32x16_bf16 v[32:47], v[4:7], v[0:3], 0
	s_waitcnt lgkmcnt(0)
	v_mfma_f32_32x32x16_bf16 v[32:47], v[8:11], v[88:91], v[32:47]
	ds_read_b128 v[4:7], v108 offset:8192
	ds_read_b128 v[8:11], v109 offset:8192
	s_waitcnt lgkmcnt(1)
	v_mfma_f32_32x32x16_bf16 v[32:47], v[4:7], v[84:87], v[32:47]
	s_waitcnt lgkmcnt(0)
	v_mfma_f32_32x32x16_bf16 v[32:47], v[8:11], v[80:83], v[32:47]
	ds_read_b128 v[4:7], v15 offset:12288
	ds_read_b128 v[8:11], v104 offset:12288
	s_waitcnt lgkmcnt(1)
	v_mfma_f32_32x32x16_bf16 v[16:31], v[4:7], v[0:3], 0
	s_waitcnt lgkmcnt(0)
	v_mfma_f32_32x32x16_bf16 v[16:31], v[8:11], v[88:91], v[16:31]
	ds_read_b128 v[4:7], v108 offset:12288
	ds_read_b128 v[8:11], v109 offset:12288
	s_waitcnt lgkmcnt(1)
	v_mfma_f32_32x32x16_bf16 v[16:31], v[4:7], v[84:87], v[16:31]
	s_waitcnt lgkmcnt(0)
	v_mfma_f32_32x32x16_bf16 v[16:31], v[8:11], v[80:83], v[16:31]
	ds_read_b128 v[4:7], v15 offset:16384
	ds_read_b128 v[104:107], v104 offset:16384
	s_waitcnt lgkmcnt(1)
	v_mfma_f32_32x32x16_bf16 v[0:15], v[4:7], v[0:3], 0
	s_waitcnt lgkmcnt(0)
	v_mfma_f32_32x32x16_bf16 v[0:15], v[104:107], v[88:91], v[0:15]
	ds_read_b128 v[88:91], v108 offset:16384
	ds_read_b128 v[104:107], v109 offset:16384
	s_waitcnt lgkmcnt(1)
	v_mfma_f32_32x32x16_bf16 v[0:15], v[88:91], v[84:87], v[0:15]
	s_waitcnt lgkmcnt(0)
	v_mfma_f32_32x32x16_bf16 v[0:15], v[104:107], v[80:83], v[0:15]
	v_lshlrev_b32_e32 v80, 2, v102
	v_add3_u32 v88, s46, v80, v92
	ds_read_b128 v[80:83], v88
	ds_read_b128 v[84:87], v88 offset:32
	s_waitcnt vmcnt(0)
	v_cvt_f32_i32_e32 v89, v103
	v_lshlrev_b32_e32 v90, 2, v101
	v_mul_f32_e32 v91, 0xbfb8aa3b, v110
	v_mul_f32_e32 v64, 0x3e38aa3b, v64
	s_waitcnt lgkmcnt(1)
	v_sub_f32_e32 v80, v89, v80
	v_fma_f32 v64, |v80|, v91, v64
	v_cmp_lt_u32_e32 vcc, v90, v100
	v_sub_f32_e32 v81, v89, v81
	v_mul_f32_e32 v65, 0x3e38aa3b, v65
	v_cndmask_b32_e32 v80, v64, v97, vcc
	v_or_b32_e32 v64, 1, v90
	v_fma_f32 v65, |v81|, v91, v65
	v_cmp_ge_u32_e64 s[2:3], v64, v100
	v_or_b32_e32 v101, 2, v90
	v_mul_f32_e32 v66, 0x3e38aa3b, v66
	v_cndmask_b32_e64 v81, v97, v65, s[2:3]
	v_sub_f32_e32 v65, v89, v82
	v_fma_f32 v65, |v65|, v91, v66
	v_cmp_ge_u32_e64 s[2:3], v101, v100
	v_or_b32_e32 v102, 3, v90
	v_mul_f32_e32 v66, 0x3e38aa3b, v67
	v_cndmask_b32_e64 v82, v97, v65, s[2:3]
	v_sub_f32_e32 v65, v89, v83
	v_fma_f32 v65, |v65|, v91, v66
	v_cmp_ge_u32_e64 s[2:3], v102, v100
	v_or_b32_e32 v103, 8, v90
	v_mul_f32_e32 v66, 0x3e38aa3b, v68
	v_cndmask_b32_e64 v83, v97, v65, s[2:3]
	s_waitcnt lgkmcnt(0)
	v_sub_f32_e32 v65, v89, v84
	v_fma_f32 v65, |v65|, v91, v66
	v_cmp_ge_u32_e64 s[2:3], v103, v100
	v_or_b32_e32 v104, 9, v90
	v_mul_f32_e32 v66, 0x3e38aa3b, v69
	v_cndmask_b32_e64 v84, v97, v65, s[2:3]
	v_sub_f32_e32 v65, v89, v85
	v_max3_f32 v64, v80, s45, v81
	v_fma_f32 v65, |v65|, v91, v66
	v_cmp_ge_u32_e64 s[2:3], v104, v100
	v_max3_f32 v64, v64, v82, v83
	v_or_b32_e32 v105, 10, v90
	v_cndmask_b32_e64 v85, v97, v65, s[2:3]
	v_max3_f32 v68, v64, v84, v85
	v_sub_f32_e32 v64, v89, v86
	v_mul_f32_e32 v65, 0x3e38aa3b, v70
	v_fma_f32 v64, |v64|, v91, v65
	v_cmp_ge_u32_e64 s[2:3], v105, v100
	v_mul_f32_e32 v65, 0x3e38aa3b, v71
	v_or_b32_e32 v106, 11, v90
	v_cndmask_b32_e64 v86, v97, v64, s[2:3]
	v_sub_f32_e32 v64, v89, v87
	v_fma_f32 v69, |v64|, v91, v65
	ds_read_b128 v[64:67], v88 offset:64
	v_cmp_ge_u32_e64 s[2:3], v106, v100
	v_or_b32_e32 v108, 16, v90
	v_mul_f32_e32 v72, 0x3e38aa3b, v72
	v_cndmask_b32_e64 v87, v97, v69, s[2:3]
	v_max3_f32 v107, v68, v86, v87
	ds_read_b128 v[68:71], v88 offset:96
	s_waitcnt lgkmcnt(1)
	v_sub_f32_e32 v64, v89, v64
	v_fma_f32 v64, |v64|, v91, v72
	v_cmp_ge_u32_e64 s[2:3], v108, v100
	v_or_b32_e32 v109, 17, v90
	v_or_b32_e32 v110, 19, v90
	v_cndmask_b32_e64 v72, v97, v64, s[2:3]
	v_sub_f32_e32 v64, v89, v65
	v_mul_f32_e32 v65, 0x3e38aa3b, v73
	v_fma_f32 v64, |v64|, v91, v65
	v_cmp_ge_u32_e64 s[2:3], v109, v100
	v_sub_f32_e32 v65, v89, v66
	v_mul_f32_e32 v66, 0x3e38aa3b, v74
	v_cndmask_b32_e64 v73, v97, v64, s[2:3]
	v_max3_f32 v64, v107, v72, v73
	v_or_b32_e32 v107, 18, v90
	v_fma_f32 v65, |v65|, v91, v66
	v_cmp_ge_u32_e64 s[2:3], v107, v100
	v_mul_f32_e32 v66, 0x3e38aa3b, v75
	v_or_b32_e32 v111, 24, v90
	v_cndmask_b32_e64 v74, v97, v65, s[2:3]
	v_sub_f32_e32 v65, v89, v67
	v_fma_f32 v65, |v65|, v91, v66
	v_cmp_ge_u32_e64 s[2:3], v110, v100
	v_mul_f32_e32 v66, 0x3e38aa3b, v76
	v_or_b32_e32 v112, 25, v90
	v_cndmask_b32_e64 v75, v97, v65, s[2:3]
	s_waitcnt lgkmcnt(0)
; #define SBAR() __builtin_amdgcn_sched_barrier(0)
; DI void unit(const bf16* __restrict__ QKV, const int* __restrict__ pos, bf16* __restrict__ OA, float* __restrict__ LSE,
;              int b, int h, int d, int r, int qb, float slope, char* lds) {
;     ...
;   for (int ta = 0; ta < 5; ++ta) {
; #pragma unroll
;     for (int g = 0; g < 4; ++g) { const f32x4 pk4 = *(const f32x4*)(pbase + ta * 32 + 8 * g);
; #pragma unroll
;       for (int j = 0; j < 4; ++j) { const int rr = 4 * g + j, kr = j + 8 * g + 4 * hi;
;         float sc = fmaf(__builtin_fabsf(pqf - pk4[j]), -sl2, p[ta][rr] * C);
;         if (ta == 0) sc = (kr >= r32) ? sc : -1e30f;
;         if (ta == 4) sc = (kr <= r32) ? sc : -1e30f;
;         p[ta][rr] = sc; mx = fmaxf(mx, sc); } }
;     SBAR(); }
	v_sub_f32_e32 v65, v89, v68
	v_fma_f32 v65, |v65|, v91, v66
	v_cmp_ge_u32_e64 s[2:3], v111, v100
	v_mul_f32_e32 v66, 0x3e38aa3b, v77
	v_or_b32_e32 v113, 26, v90
	v_cndmask_b32_e64 v76, v97, v65, s[2:3]
	v_sub_f32_e32 v65, v89, v69
	v_fma_f32 v65, |v65|, v91, v66
	v_cmp_ge_u32_e64 s[2:3], v112, v100
	v_mul_f32_e32 v66, 0x3e38aa3b, v78
	v_or_b32_e32 v114, 27, v90
	v_cndmask_b32_e64 v77, v97, v65, s[2:3]
	v_sub_f32_e32 v65, v89, v70
	v_fma_f32 v65, |v65|, v91, v66
	v_cmp_ge_u32_e64 s[2:3], v113, v100
	v_mul_f32_e32 v66, 0x3e38aa3b, v79
	v_max3_f32 v64, v64, v74, v75
	v_cndmask_b32_e64 v78, v97, v65, s[2:3]
	v_sub_f32_e32 v65, v89, v71
	v_fma_f32 v65, |v65|, v91, v66
	v_cmp_ge_u32_e64 s[2:3], v114, v100
	v_max3_f32 v64, v64, v76, v77
	s_nop 0
	v_cndmask_b32_e64 v79, v97, v65, s[2:3]
	v_max3_f32 v115, v64, v78, v79
	ds_read_b128 v[64:67], v88 offset:128
	ds_read_b128 v[68:71], v88 offset:160
	v_mul_f32_e32 v49, 0x3e38aa3b, v49
	v_mul_f32_e32 v50, 0x3e38aa3b, v50
	v_mul_f32_e32 v48, 0x3e38aa3b, v48
	s_waitcnt lgkmcnt(1)
	v_sub_f32_e32 v65, v89, v65
	v_fma_f32 v65, |v65|, v91, v49
	v_sub_f32_e32 v49, v89, v66
	v_sub_f32_e32 v64, v89, v64
	v_fma_f32 v66, |v49|, v91, v50
	v_sub_f32_e32 v49, v89, v67
	v_mul_f32_e32 v50, 0x3e38aa3b, v51
	v_fma_f32 v64, |v64|, v91, v48
	v_fma_f32 v67, |v49|, v91, v50
	s_waitcnt lgkmcnt(0)
	v_sub_f32_e32 v49, v89, v68
	v_mul_f32_e32 v50, 0x3e38aa3b, v52
	v_max3_f32 v48, v115, v64, v65
	v_fma_f32 v68, |v49|, v91, v50
	v_sub_f32_e32 v49, v89, v69
	v_mul_f32_e32 v50, 0x3e38aa3b, v53
	v_max3_f32 v48, v48, v66, v67
	v_fma_f32 v69, |v49|, v91, v50
	v_max3_f32 v52, v48, v68, v69
	v_sub_f32_e32 v48, v89, v70
	v_mul_f32_e32 v49, 0x3e38aa3b, v54
	v_fma_f32 v70, |v48|, v91, v49
	ds_read_b128 v[48:51], v88 offset:192
	v_sub_f32_e32 v53, v89, v71
	v_mul_f32_e32 v54, 0x3e38aa3b, v55
	v_fma_f32 v71, |v53|, v91, v54
	v_max3_f32 v115, v52, v70, v71
	ds_read_b128 v[52:55], v88 offset:224
	s_waitcnt lgkmcnt(1)
	v_sub_f32_e32 v48, v89, v48
	v_mul_f32_e32 v56, 0x3e38aa3b, v56
	v_fma_f32 v56, |v48|, v91, v56
	v_sub_f32_e32 v48, v89, v49
	v_mul_f32_e32 v49, 0x3e38aa3b, v57
	v_fma_f32 v57, |v48|, v91, v49
	v_sub_f32_e32 v49, v89, v50
	v_mul_f32_e32 v50, 0x3e38aa3b, v58
	v_fma_f32 v58, |v49|, v91, v50
	v_sub_f32_e32 v49, v89, v51
	v_mul_f32_e32 v50, 0x3e38aa3b, v59
	v_fma_f32 v59, |v49|, v91, v50
	s_waitcnt lgkmcnt(0)
	v_sub_f32_e32 v49, v89, v52
	v_mul_f32_e32 v50, 0x3e38aa3b, v60
	v_fma_f32 v60, |v49|, v91, v50
	v_sub_f32_e32 v49, v89, v53
	v_mul_f32_e32 v50, 0x3e38aa3b, v61
	v_max3_f32 v48, v115, v56, v57
	v_fma_f32 v61, |v49|, v91, v50
	v_sub_f32_e32 v49, v89, v54
	v_mul_f32_e32 v50, 0x3e38aa3b, v62
	v_max3_f32 v48, v48, v58, v59
	v_fma_f32 v62, |v49|, v91, v50
	v_sub_f32_e32 v49, v89, v55
	v_mul_f32_e32 v50, 0x3e38aa3b, v63
	v_max3_f32 v48, v48, v60, v61
	v_fma_f32 v63, |v49|, v91, v50
	v_max3_f32 v115, v48, v62, v63
	ds_read_b128 v[48:51], v88 offset:256
	ds_read_b128 v[52:55], v88 offset:288
	v_mul_f32_e32 v33, 0x3e38aa3b, v33
	v_mul_f32_e32 v34, 0x3e38aa3b, v34
	v_mul_f32_e32 v32, 0x3e38aa3b, v32
	s_waitcnt lgkmcnt(1)
	v_sub_f32_e32 v49, v89, v49
	v_fma_f32 v49, |v49|, v91, v33
	v_sub_f32_e32 v33, v89, v50
	v_sub_f32_e32 v48, v89, v48
	v_fma_f32 v50, |v33|, v91, v34
	v_sub_f32_e32 v33, v89, v51
	v_mul_f32_e32 v34, 0x3e38aa3b, v35
	v_fma_f32 v48, |v48|, v91, v32
	v_fma_f32 v51, |v33|, v91, v34
	s_waitcnt lgkmcnt(0)
	v_sub_f32_e32 v33, v89, v52
	v_mul_f32_e32 v34, 0x3e38aa3b, v36
	v_max3_f32 v32, v115, v48, v49
	v_fma_f32 v52, |v33|, v91, v34
	v_sub_f32_e32 v33, v89, v53
	v_mul_f32_e32 v34, 0x3e38aa3b, v37
	v_max3_f32 v32, v32, v50, v51
	v_fma_f32 v53, |v33|, v91, v34
	v_max3_f32 v36, v32, v52, v53
	v_sub_f32_e32 v32, v89, v54
	v_mul_f32_e32 v33, 0x3e38aa3b, v38
	v_fma_f32 v54, |v32|, v91, v33
	ds_read_b128 v[32:35], v88 offset:320
	v_sub_f32_e32 v37, v89, v55
	v_mul_f32_e32 v38, 0x3e38aa3b, v39
	v_fma_f32 v55, |v37|, v91, v38
	v_max3_f32 v115, v36, v54, v55
	ds_read_b128 v[36:39], v88 offset:352
	s_waitcnt lgkmcnt(1)
	v_sub_f32_e32 v32, v89, v32
	v_mul_f32_e32 v40, 0x3e38aa3b, v40
	v_fma_f32 v40, |v32|, v91, v40
	v_sub_f32_e32 v32, v89, v33
	v_mul_f32_e32 v33, 0x3e38aa3b, v41
	v_fma_f32 v41, |v32|, v91, v33
	v_sub_f32_e32 v33, v89, v34
	v_mul_f32_e32 v34, 0x3e38aa3b, v42
	v_fma_f32 v42, |v33|, v91, v34
	v_sub_f32_e32 v33, v89, v35
	v_mul_f32_e32 v34, 0x3e38aa3b, v43
	v_fma_f32 v43, |v33|, v91, v34
	s_waitcnt lgkmcnt(0)
	v_sub_f32_e32 v33, v89, v36
	v_mul_f32_e32 v34, 0x3e38aa3b, v44
	v_fma_f32 v44, |v33|, v91, v34
	v_sub_f32_e32 v33, v89, v37
	v_mul_f32_e32 v34, 0x3e38aa3b, v45
	v_max3_f32 v32, v115, v40, v41
	v_fma_f32 v45, |v33|, v91, v34
	v_sub_f32_e32 v33, v89, v38
	v_mul_f32_e32 v34, 0x3e38aa3b, v46
	v_max3_f32 v32, v32, v42, v43
	v_fma_f32 v46, |v33|, v91, v34
	v_sub_f32_e32 v33, v89, v39
	v_mul_f32_e32 v34, 0x3e38aa3b, v47
	v_max3_f32 v32, v32, v44, v45
	v_fma_f32 v47, |v33|, v91, v34
	v_max3_f32 v115, v32, v46, v47
	ds_read_b128 v[32:35], v88 offset:384
	ds_read_b128 v[36:39], v88 offset:416
	v_mul_f32_e32 v17, 0x3e38aa3b, v17
	v_mul_f32_e32 v18, 0x3e38aa3b, v18
	v_mul_f32_e32 v16, 0x3e38aa3b, v16
	s_waitcnt lgkmcnt(1)
	v_sub_f32_e32 v33, v89, v33
	v_fma_f32 v33, |v33|, v91, v17
	v_sub_f32_e32 v17, v89, v34
	v_sub_f32_e32 v32, v89, v32
	v_fma_f32 v34, |v17|, v91, v18
	v_sub_f32_e32 v17, v89, v35
	v_mul_f32_e32 v18, 0x3e38aa3b, v19
	v_fma_f32 v116, |v32|, v91, v16
	v_fma_f32 v35, |v17|, v91, v18
	s_waitcnt lgkmcnt(0)
; #define SBAR() __builtin_amdgcn_sched_barrier(0)
; DI void unit(const bf16* __restrict__ QKV, const int* __restrict__ pos, bf16* __restrict__ OA, float* __restrict__ LSE,
;              int b, int h, int d, int r, int qb, float slope, char* lds) {
;     ...
;   for (int ta = 0; ta < 5; ++ta) {
; #pragma unroll
;     for (int g = 0; g < 4; ++g) { const f32x4 pk4 = *(const f32x4*)(pbase + ta * 32 + 8 * g);
; #pragma unroll
;       for (int j = 0; j < 4; ++j) { const int rr = 4 * g + j, kr = j + 8 * g + 4 * hi;
;         float sc = fmaf(__builtin_fabsf(pqf - pk4[j]), -sl2, p[ta][rr] * C);
;         if (ta == 0) sc = (kr >= r32) ? sc : -1e30f;
;         if (ta == 4) sc = (kr <= r32) ? sc : -1e30f;
;         p[ta][rr] = sc; mx = fmaxf(mx, sc); } }
;     SBAR(); }
;   { auto x = __builtin_amdgcn_permlane32_swap(__float_as_uint(mx), __float_as_uint(mx), false, false); mx = fmaxf(__uint_as_float(x[0]), __uint_as_float(x[1])); }
;   float ls = 0.f;
; #pragma unroll
;   for (int ta = 0; ta < 5; ++ta)
; #pragma unroll
;     for (int rr = 0; rr < 16; ++rr) { p[ta][rr] = __builtin_amdgcn_exp2f(p[ta][rr] - mx); ls += p[ta][rr]; if (rr == 15) SBAR(); }
;   { auto x = __builtin_amdgcn_permlane32_swap(__float_as_uint(ls), __float_as_uint(ls), false, false); ls = __uint_as_float(x[0]) + __uint_as_float(x[1]); }
	v_sub_f32_e32 v17, v89, v36
	v_mul_f32_e32 v18, 0x3e38aa3b, v20
	v_max3_f32 v16, v115, v116, v33
	v_fma_f32 v36, |v17|, v91, v18
	v_sub_f32_e32 v17, v89, v37
	v_mul_f32_e32 v18, 0x3e38aa3b, v21
	v_max3_f32 v16, v16, v34, v35
	v_fma_f32 v37, |v17|, v91, v18
	v_max3_f32 v20, v16, v36, v37
	v_sub_f32_e32 v16, v89, v38
	v_mul_f32_e32 v17, 0x3e38aa3b, v22
	v_fma_f32 v38, |v16|, v91, v17
	ds_read_b128 v[16:19], v88 offset:448
	v_sub_f32_e32 v21, v89, v39
	v_mul_f32_e32 v22, 0x3e38aa3b, v23
	v_fma_f32 v39, |v21|, v91, v22
	v_max3_f32 v32, v20, v38, v39
	ds_read_b128 v[20:23], v88 offset:480
	s_waitcnt lgkmcnt(1)
	v_sub_f32_e32 v16, v89, v16
	v_mul_f32_e32 v24, 0x3e38aa3b, v24
	v_fma_f32 v24, |v16|, v91, v24
	v_sub_f32_e32 v16, v89, v17
	v_mul_f32_e32 v17, 0x3e38aa3b, v25
	v_fma_f32 v25, |v16|, v91, v17
	v_sub_f32_e32 v17, v89, v18
	v_mul_f32_e32 v18, 0x3e38aa3b, v26
	v_fma_f32 v26, |v17|, v91, v18
	v_sub_f32_e32 v17, v89, v19
	v_mul_f32_e32 v18, 0x3e38aa3b, v27
	v_fma_f32 v27, |v17|, v91, v18
	s_waitcnt lgkmcnt(0)
	v_sub_f32_e32 v17, v89, v20
	v_mul_f32_e32 v18, 0x3e38aa3b, v28
	v_fma_f32 v28, |v17|, v91, v18
	v_sub_f32_e32 v17, v89, v21
	v_mul_f32_e32 v18, 0x3e38aa3b, v29
	v_max3_f32 v16, v32, v24, v25
	v_fma_f32 v29, |v17|, v91, v18
	v_sub_f32_e32 v17, v89, v22
	v_mul_f32_e32 v18, 0x3e38aa3b, v30
	v_max3_f32 v16, v16, v26, v27
	v_fma_f32 v30, |v17|, v91, v18
	v_sub_f32_e32 v17, v89, v23
	v_mul_f32_e32 v18, 0x3e38aa3b, v31
	v_max3_f32 v16, v16, v28, v29
	v_fma_f32 v31, |v17|, v91, v18
	v_max3_f32 v32, v16, v30, v31
	ds_read_b128 v[16:19], v88 offset:512
	ds_read_b128 v[20:23], v88 offset:544
	v_mul_f32_e32 v0, 0x3e38aa3b, v0
	v_cmp_le_u32_e64 s[2:3], v90, v100
	v_mul_f32_e32 v2, 0x3e38aa3b, v2
	s_waitcnt lgkmcnt(1)
	v_sub_f32_e32 v16, v89, v16
	v_fma_f32 v0, |v16|, v91, v0
	v_sub_f32_e32 v17, v89, v17
	v_cndmask_b32_e64 v16, v97, v0, s[2:3]
	v_mul_f32_e32 v0, 0x3e38aa3b, v1
	v_fma_f32 v0, |v17|, v91, v0
	v_sub_f32_e32 v1, v89, v18
	v_cndmask_b32_e32 v17, v97, v0, vcc
	v_fma_f32 v1, |v1|, v91, v2
	v_cmp_le_u32_e32 vcc, v101, v100
	v_mul_f32_e32 v2, 0x3e38aa3b, v3
	v_max3_f32 v0, v32, v16, v17
	v_cndmask_b32_e32 v18, v97, v1, vcc
	v_sub_f32_e32 v1, v89, v19
	v_fma_f32 v1, |v1|, v91, v2
	v_cmp_le_u32_e32 vcc, v102, v100
	v_mul_f32_e32 v2, 0x3e38aa3b, v4
	v_mul_f32_e32 v8, 0x3e38aa3b, v8
	v_cndmask_b32_e32 v19, v97, v1, vcc
	s_waitcnt lgkmcnt(0)
	v_sub_f32_e32 v1, v89, v20
	v_fma_f32 v1, |v1|, v91, v2
	v_cmp_le_u32_e32 vcc, v103, v100
	v_mul_f32_e32 v2, 0x3e38aa3b, v5
	v_max3_f32 v0, v0, v18, v19
	v_cndmask_b32_e32 v20, v97, v1, vcc
	v_sub_f32_e32 v1, v89, v21
	v_fma_f32 v1, |v1|, v91, v2
	v_cmp_le_u32_e32 vcc, v104, v100
	s_nop 1
	v_cndmask_b32_e32 v21, v97, v1, vcc
	v_max3_f32 v4, v0, v20, v21
	v_sub_f32_e32 v0, v89, v22
	v_mul_f32_e32 v1, 0x3e38aa3b, v6
	v_fma_f32 v0, |v0|, v91, v1
	v_cmp_le_u32_e32 vcc, v105, v100
	v_mul_f32_e32 v1, 0x3e38aa3b, v7
	s_nop 0
	v_cndmask_b32_e32 v22, v97, v0, vcc
	v_sub_f32_e32 v0, v89, v23
	v_fma_f32 v5, |v0|, v91, v1
	ds_read_b128 v[0:3], v88 offset:576
	v_cmp_le_u32_e32 vcc, v106, v100
	s_nop 1
	v_cndmask_b32_e32 v23, v97, v5, vcc
	v_max3_f32 v32, v4, v22, v23
	ds_read_b128 v[4:7], v88 offset:608
	s_waitcnt lgkmcnt(1)
	v_sub_f32_e32 v0, v89, v0
	v_fma_f32 v0, |v0|, v91, v8
	v_cmp_le_u32_e32 vcc, v108, v100
	v_sub_f32_e32 v1, v89, v1
	v_mul_f32_e32 v8, 0x3e38aa3b, v9
	v_cndmask_b32_e32 v0, v97, v0, vcc
	v_fma_f32 v1, |v1|, v91, v8
	v_cmp_le_u32_e32 vcc, v109, v100
	v_sub_f32_e32 v2, v89, v2
	v_mul_f32_e32 v9, 0x3e38aa3b, v10
	v_cndmask_b32_e32 v1, v97, v1, vcc
	v_fma_f32 v2, |v2|, v91, v9
	v_cmp_le_u32_e32 vcc, v107, v100
	v_sub_f32_e32 v3, v89, v3
	v_mul_f32_e32 v9, 0x3e38aa3b, v11
	v_cndmask_b32_e32 v2, v97, v2, vcc
	v_fma_f32 v3, |v3|, v91, v9
	v_cmp_le_u32_e32 vcc, v110, v100
	s_waitcnt lgkmcnt(0)
	v_sub_f32_e32 v4, v89, v4
	v_mul_f32_e32 v9, 0x3e38aa3b, v12
	v_cndmask_b32_e32 v3, v97, v3, vcc
	v_fma_f32 v4, |v4|, v91, v9
	v_cmp_le_u32_e32 vcc, v111, v100
	v_sub_f32_e32 v5, v89, v5
	v_mul_f32_e32 v9, 0x3e38aa3b, v13
	v_cndmask_b32_e32 v4, v97, v4, vcc
	v_fma_f32 v5, |v5|, v91, v9
	v_cmp_le_u32_e32 vcc, v112, v100
	v_sub_f32_e32 v6, v89, v6
	v_mul_f32_e32 v9, 0x3e38aa3b, v14
	v_max3_f32 v8, v32, v0, v1
	v_cndmask_b32_e32 v5, v97, v5, vcc
	v_fma_f32 v6, |v6|, v91, v9
	v_cmp_le_u32_e32 vcc, v113, v100
	v_sub_f32_e32 v7, v89, v7
	v_mul_f32_e32 v9, 0x3e38aa3b, v15
	v_max3_f32 v8, v8, v2, v3
	v_cndmask_b32_e32 v6, v97, v6, vcc
	v_fma_f32 v7, |v7|, v91, v9
	v_cmp_le_u32_e32 vcc, v114, v100
	v_max3_f32 v8, v8, v4, v5
	s_nop 0
	v_cndmask_b32_e32 v7, v97, v7, vcc
	v_max3_f32 v8, v8, v6, v7
	v_mov_b32_e32 v9, v8
	s_nop 1
	v_permlane32_swap_b32_e32 v8, v9
	v_max_f32_e32 v9, v9, v9
	v_max_f32_e32 v8, v8, v8
	v_max_f32_e32 v32, v8, v9
	v_sub_f32_e32 v8, v80, v32
	v_exp_f32_e32 v8, v8
	v_sub_f32_e32 v9, v81, v32
	v_exp_f32_e32 v9, v9
	v_sub_f32_e32 v10, v82, v32
	v_exp_f32_e32 v10, v10
	v_sub_f32_e32 v11, v83, v32
	v_exp_f32_e32 v11, v11
	v_sub_f32_e32 v12, v84, v32
	v_exp_f32_e32 v12, v12
	v_sub_f32_e32 v13, v85, v32
	v_add_f32_e32 v80, 0, v8
	v_exp_f32_e32 v13, v13
	v_sub_f32_e32 v14, v86, v32
	v_add_f32_e32 v80, v9, v80
	v_exp_f32_e32 v14, v14
	v_sub_f32_e32 v15, v87, v32
	v_add_f32_e32 v80, v10, v80
	v_exp_f32_e32 v15, v15
	v_sub_f32_e32 v72, v72, v32
	v_add_f32_e32 v80, v11, v80
	v_exp_f32_e32 v72, v72
	v_sub_f32_e32 v73, v73, v32
	v_add_f32_e32 v80, v12, v80
	v_exp_f32_e32 v73, v73
	v_sub_f32_e32 v74, v74, v32
	v_add_f32_e32 v80, v13, v80
	v_exp_f32_e32 v74, v74
	v_sub_f32_e32 v75, v75, v32
	v_add_f32_e32 v80, v14, v80
	v_exp_f32_e32 v75, v75
	v_sub_f32_e32 v76, v76, v32
	v_add_f32_e32 v80, v15, v80
	v_exp_f32_e32 v76, v76
; #define SBAR() __builtin_amdgcn_sched_barrier(0)
; DI int v_rd_base(int lane) { return ((lane & 3) << 3) | (((lane >> 2) & 3) << 6) | (((lane >> 4) & 1) << 5) | (((lane >> 5) & 1) << 8); }
; DI s16x4 vtr(const char* p) { return __builtin_bit_cast(s16x4, __builtin_amdgcn_ds_read_tr16_b64_v4i16((LAS v4i16_t*)(uintptr_t)p)); }
; DI void unit(const bf16* __restrict__ QKV, const int* __restrict__ pos, bf16* __restrict__ OA, float* __restrict__ LSE,
;              int b, int h, int d, int r, int qb, float slope, char* lds) {
;     ...
;   float ls = 0.f;
; #pragma unroll
;   for (int ta = 0; ta < 5; ++ta)
; #pragma unroll
;     for (int rr = 0; rr < 16; ++rr) { p[ta][rr] = __builtin_amdgcn_exp2f(p[ta][rr] - mx); ls += p[ta][rr]; if (rr == 15) SBAR(); }
;   { auto x = __builtin_amdgcn_permlane32_swap(__float_as_uint(ls), __float_as_uint(ls), false, false); ls = __uint_as_float(x[0]) + __uint_as_float(x[1]); }
;   f32x16 o[2] = {};
;   const char* vb = V_lds + att::v_rd_base(lane) + wid * 2 * 2048;
; #pragma unroll
;   for (int ta = 0; ta < 5; ++ta) {
;     bf16x8 pa0, pa1; PK4(p[ta], 0, pa0); PK4(p[ta], 8, pa1);
; #pragma unroll
;     for (int d0 = 0; d0 < 2; ++d0) {
;       const s16x4 l0 = vtr(vb + (2 * ta) * 2048 + d0 * 512), h0 = vtr(vb + (2 * ta) * 2048 + 1024 + d0 * 512);
	v_sub_f32_e32 v77, v77, v32
	v_add_f32_e32 v80, v72, v80
	v_exp_f32_e32 v77, v77
	v_sub_f32_e32 v78, v78, v32
	v_add_f32_e32 v80, v73, v80
	v_exp_f32_e32 v78, v78
	v_add_f32_e32 v80, v74, v80
	v_sub_f32_e32 v79, v79, v32
	v_add_f32_e32 v80, v75, v80
	v_exp_f32_e32 v79, v79
	v_add_f32_e32 v80, v76, v80
	v_add_f32_e32 v80, v77, v80
	v_add_f32_e32 v80, v78, v80
	v_add_f32_e32 v80, v79, v80
	v_sub_f32_e32 v64, v64, v32
	v_exp_f32_e32 v64, v64
	v_sub_f32_e32 v65, v65, v32
	v_exp_f32_e32 v65, v65
	v_sub_f32_e32 v66, v66, v32
	v_exp_f32_e32 v66, v66
	v_sub_f32_e32 v67, v67, v32
	v_exp_f32_e32 v67, v67
	v_sub_f32_e32 v68, v68, v32
	v_exp_f32_e32 v68, v68
	v_sub_f32_e32 v69, v69, v32
	v_add_f32_e32 v80, v64, v80
	v_exp_f32_e32 v69, v69
	v_sub_f32_e32 v70, v70, v32
	v_add_f32_e32 v80, v65, v80
	v_exp_f32_e32 v70, v70
	v_sub_f32_e32 v71, v71, v32
	v_add_f32_e32 v80, v66, v80
	v_exp_f32_e32 v71, v71
	v_sub_f32_e32 v56, v56, v32
	v_add_f32_e32 v80, v67, v80
	v_exp_f32_e32 v56, v56
	v_sub_f32_e32 v57, v57, v32
	v_add_f32_e32 v80, v68, v80
	v_exp_f32_e32 v57, v57
	v_sub_f32_e32 v58, v58, v32
	v_add_f32_e32 v80, v69, v80
	v_exp_f32_e32 v58, v58
	v_sub_f32_e32 v59, v59, v32
	v_add_f32_e32 v80, v70, v80
	v_exp_f32_e32 v59, v59
	v_sub_f32_e32 v60, v60, v32
	v_add_f32_e32 v80, v71, v80
	v_exp_f32_e32 v60, v60
	v_sub_f32_e32 v61, v61, v32
	v_add_f32_e32 v80, v56, v80
	v_exp_f32_e32 v61, v61
	v_sub_f32_e32 v62, v62, v32
	v_add_f32_e32 v80, v57, v80
	v_exp_f32_e32 v62, v62
	v_add_f32_e32 v80, v58, v80
	v_sub_f32_e32 v63, v63, v32
	v_add_f32_e32 v80, v59, v80
	v_exp_f32_e32 v63, v63
	v_add_f32_e32 v80, v60, v80
	v_add_f32_e32 v80, v61, v80
	v_add_f32_e32 v80, v62, v80
	v_add_f32_e32 v80, v63, v80
	v_sub_f32_e32 v40, v40, v32
	v_exp_f32_e32 v87, v40
	v_sub_f32_e32 v40, v41, v32
	v_sub_f32_e32 v48, v48, v32
	v_exp_f32_e32 v88, v40
	v_sub_f32_e32 v40, v42, v32
	v_exp_f32_e32 v81, v48
	v_sub_f32_e32 v48, v49, v32
	v_exp_f32_e32 v89, v40
	v_sub_f32_e32 v40, v43, v32
	v_exp_f32_e32 v82, v48
	v_sub_f32_e32 v48, v50, v32
	v_exp_f32_e32 v90, v40
	v_sub_f32_e32 v40, v44, v32
	v_exp_f32_e32 v83, v48
	v_sub_f32_e32 v48, v51, v32
	v_exp_f32_e32 v91, v40
	v_sub_f32_e32 v40, v45, v32
	v_exp_f32_e32 v84, v48
	v_sub_f32_e32 v48, v52, v32
	v_exp_f32_e32 v100, v40
	v_sub_f32_e32 v40, v46, v32
	v_exp_f32_e32 v85, v48
	v_sub_f32_e32 v48, v53, v32
	v_exp_f32_e32 v101, v40
	v_add_f32_e32 v40, v81, v80
	v_exp_f32_e32 v86, v48
	v_sub_f32_e32 v48, v54, v32
	v_add_f32_e32 v40, v82, v40
	v_exp_f32_e32 v54, v48
	v_sub_f32_e32 v48, v55, v32
	v_add_f32_e32 v40, v83, v40
	v_exp_f32_e32 v55, v48
	v_add_f32_e32 v40, v84, v40
	v_add_f32_e32 v40, v85, v40
	v_add_f32_e32 v40, v86, v40
	v_add_f32_e32 v40, v54, v40
	v_add_f32_e32 v40, v55, v40
	v_add_f32_e32 v40, v87, v40
	v_add_f32_e32 v40, v88, v40
	v_add_f32_e32 v40, v89, v40
	v_sub_f32_e32 v41, v47, v32
	v_add_f32_e32 v40, v90, v40
	v_exp_f32_e32 v80, v41
	v_add_f32_e32 v40, v91, v40
	v_add_f32_e32 v40, v100, v40
	v_add_f32_e32 v40, v101, v40
	v_add_f32_e32 v40, v80, v40
	v_sub_f32_e32 v24, v24, v32
	v_exp_f32_e32 v109, v24
	v_sub_f32_e32 v24, v25, v32
	v_sub_f32_e32 v41, v116, v32
	v_exp_f32_e32 v110, v24
	v_sub_f32_e32 v24, v26, v32
	v_exp_f32_e32 v102, v41
	v_sub_f32_e32 v33, v33, v32
	v_exp_f32_e32 v111, v24
	v_sub_f32_e32 v24, v27, v32
	v_exp_f32_e32 v33, v33
	v_sub_f32_e32 v34, v34, v32
	v_exp_f32_e32 v112, v24
	v_sub_f32_e32 v24, v28, v32
	v_exp_f32_e32 v103, v34
	v_sub_f32_e32 v34, v35, v32
	v_exp_f32_e32 v113, v24
	v_sub_f32_e32 v24, v29, v32
	v_exp_f32_e32 v104, v34
	v_sub_f32_e32 v34, v36, v32
	v_exp_f32_e32 v114, v24
	v_sub_f32_e32 v24, v30, v32
	v_exp_f32_e32 v105, v34
	v_sub_f32_e32 v34, v37, v32
	v_exp_f32_e32 v115, v24
	v_add_f32_e32 v24, v102, v40
	v_exp_f32_e32 v106, v34
	v_sub_f32_e32 v34, v38, v32
	v_add_f32_e32 v24, v33, v24
	v_exp_f32_e32 v107, v34
	v_sub_f32_e32 v34, v39, v32
	v_add_f32_e32 v24, v103, v24
	v_exp_f32_e32 v108, v34
	v_add_f32_e32 v24, v104, v24
	v_add_f32_e32 v24, v105, v24
	v_add_f32_e32 v24, v106, v24
	v_add_f32_e32 v24, v107, v24
	v_add_f32_e32 v24, v108, v24
	v_add_f32_e32 v24, v109, v24
	v_add_f32_e32 v24, v110, v24
	v_add_f32_e32 v24, v111, v24
	v_sub_f32_e32 v25, v31, v32
	v_add_f32_e32 v24, v112, v24
	v_exp_f32_e32 v116, v25
	v_add_f32_e32 v24, v113, v24
	v_add_f32_e32 v24, v114, v24
	v_add_f32_e32 v24, v115, v24
	v_add_f32_e32 v24, v116, v24
	v_sub_f32_e32 v0, v0, v32
	v_exp_f32_e32 v125, v0
	v_sub_f32_e32 v0, v1, v32
	v_sub_f32_e32 v16, v16, v32
	v_exp_f32_e32 v126, v0
	v_sub_f32_e32 v0, v2, v32
	v_exp_f32_e32 v117, v16
	v_sub_f32_e32 v16, v17, v32
	v_exp_f32_e32 v127, v0
	v_sub_f32_e32 v0, v3, v32
	v_exp_f32_e32 v118, v16
	v_sub_f32_e32 v16, v18, v32
	v_exp_f32_e32 v128, v0
	v_sub_f32_e32 v0, v4, v32
	v_exp_f32_e32 v119, v16
	v_sub_f32_e32 v16, v19, v32
	v_exp_f32_e32 v129, v0
	v_sub_f32_e32 v0, v5, v32
	v_exp_f32_e32 v120, v16
	v_sub_f32_e32 v16, v20, v32
	v_exp_f32_e32 v130, v0
	v_sub_f32_e32 v0, v6, v32
	v_exp_f32_e32 v121, v16
	v_sub_f32_e32 v16, v21, v32
	v_exp_f32_e32 v131, v0
	v_add_f32_e32 v0, v117, v24
	v_exp_f32_e32 v122, v16
	v_sub_f32_e32 v16, v22, v32
	v_add_f32_e32 v0, v118, v0
	v_exp_f32_e32 v123, v16
	v_sub_f32_e32 v16, v23, v32
	v_add_f32_e32 v0, v119, v0
	v_exp_f32_e32 v124, v16
	v_add_f32_e32 v0, v120, v0
	v_add_f32_e32 v0, v121, v0
	v_add_f32_e32 v0, v122, v0
	v_add_f32_e32 v0, v123, v0
	v_add_f32_e32 v0, v124, v0
	v_add_f32_e32 v0, v125, v0
	v_add_f32_e32 v0, v126, v0
	v_add_f32_e32 v0, v127, v0
	v_sub_f32_e32 v1, v7, v32
	v_add_f32_e32 v0, v128, v0
	v_exp_f32_e32 v132, v1
	v_add_f32_e32 v0, v129, v0
	v_add_f32_e32 v0, v130, v0
	v_add_f32_e32 v0, v131, v0
	v_add_f32_e32 v133, v132, v0
	v_lshlrev_b32_e32 v0, 3, v98
	v_and_b32_e32 v1, 24, v0
	v_lshlrev_b32_e32 v2, 4, v98
	v_lshlrev_b32_e32 v3, 1, v98
	v_and_b32_e32 v2, 0xc0, v2
	v_and_b32_e32 v3, 32, v3
	v_add_u32_e32 v1, 0, v1
	v_and_b32_e32 v0, 0x100, v0
	v_add3_u32 v1, v1, v2, v3
	v_add3_u32 v99, v1, v0, v99
	v_cvt_pk_bf16_f32 v0, v8, v9
	v_cvt_pk_bf16_f32 v1, v10, v11
	v_cvt_pk_bf16_f32 v2, v12, v13
	v_cvt_pk_bf16_f32 v3, v14, v15
	v_cvt_pk_bf16_f32 v34, v72, v73
	v_cvt_pk_bf16_f32 v35, v74, v75
	v_cvt_pk_bf16_f32 v36, v76, v77
	v_cvt_pk_bf16_f32 v37, v78, v79
	ds_read_b64_tr_b16 v[4:5], v99 offset:49152
	ds_read_b64_tr_b16 v[6:7], v99 offset:50176
	v_permlane32_swap_b32_e32 v0, v2
	v_permlane32_swap_b32_e32 v1, v3
	ds_read_b64_tr_b16 v[10:11], v99 offset:50688
	ds_read_b64_tr_b16 v[8:9], v99 offset:49664
	s_waitcnt lgkmcnt(2)
; #define SBAR() __builtin_amdgcn_sched_barrier(0)
; DI int v_rd_base(int lane) { return ((lane & 3) << 3) | (((lane >> 2) & 3) << 6) | (((lane >> 4) & 1) << 5) | (((lane >> 5) & 1) << 8); }
; DI s16x4 vtr(const char* p) { return __builtin_bit_cast(s16x4, __builtin_amdgcn_ds_read_tr16_b64_v4i16((LAS v4i16_t*)(uintptr_t)p)); }
; DI void unit(const bf16* __restrict__ QKV, const int* __restrict__ pos, bf16* __restrict__ OA, float* __restrict__ LSE,
;              int b, int h, int d, int r, int qb, float slope, char* lds) {
;     ...
;   f32x16 o[2] = {};
;   const char* vb = V_lds + att::v_rd_base(lane) + wid * 2 * 2048;
; #pragma unroll
;   for (int ta = 0; ta < 5; ++ta) {
;     bf16x8 pa0, pa1; PK4(p[ta], 0, pa0); PK4(p[ta], 8, pa1);
; #pragma unroll
;     for (int d0 = 0; d0 < 2; ++d0) {
;       const s16x4 l0 = vtr(vb + (2 * ta) * 2048 + d0 * 512), h0 = vtr(vb + (2 * ta) * 2048 + 1024 + d0 * 512);
;       const s16x4 l1 = vtr(vb + (2 * ta + 1) * 2048 + d0 * 512), h1 = vtr(vb + (2 * ta + 1) * 2048 + 1024 + d0 * 512);
;       o[d0] = __builtin_amdgcn_mfma_f32_32x32x16_bf16((bf16x8){l0[0], l0[1], l0[2], l0[3], h0[0], h0[1], h0[2], h0[3]}, pa0, o[d0], 0, 0, 0);
;       o[d0] = __builtin_amdgcn_mfma_f32_32x32x16_bf16((bf16x8){l1[0], l1[1], l1[2], l1[3], h1[0], h1[1], h1[2], h1[3]}, pa1, o[d0], 0, 0, 0);
;     }
;     SBAR();
;   }
;   if (hi == 0) LSE[(size_t)(b * SEQ + tq) * 8 + h] = (mx + __builtin_amdgcn_logf(ls)) * 0.6931471805599453f;
	v_mfma_f32_32x32x16_bf16 v[16:31], v[4:7], v[0:3], 0
	ds_read_b64_tr_b16 v[4:5], v99 offset:51200
	ds_read_b64_tr_b16 v[6:7], v99 offset:52224
	v_permlane32_swap_b32_e32 v34, v36
	v_permlane32_swap_b32_e32 v35, v37
	ds_read_b64_tr_b16 v[40:41], v99 offset:52736
	ds_read_b64_tr_b16 v[38:39], v99 offset:51712
	v_mov_b32_e32 v72, v133
	s_waitcnt lgkmcnt(2)
	v_mfma_f32_32x32x16_bf16 v[16:31], v[4:7], v[34:37], v[16:31]
	v_permlane32_swap_b32_e32 v133, v72
	v_add_u32_e32 v73, 0xc000, v99
	v_mfma_f32_32x32x16_bf16 v[0:15], v[8:11], v[0:3], 0
	s_waitcnt lgkmcnt(0)
	v_mfma_f32_32x32x16_bf16 v[0:15], v[38:41], v[34:37], v[0:15]
	v_cvt_pk_bf16_f32 v34, v64, v65
	v_cvt_pk_bf16_f32 v35, v66, v67
	v_cvt_pk_bf16_f32 v36, v68, v69
	v_cvt_pk_bf16_f32 v37, v70, v71
	v_cvt_pk_bf16_f32 v38, v56, v57
	v_cvt_pk_bf16_f32 v39, v58, v59
	v_cvt_pk_bf16_f32 v40, v60, v61
	v_cvt_pk_bf16_f32 v41, v62, v63
	ds_read_b64_tr_b16 v[42:43], v99 offset:53248
	ds_read_b64_tr_b16 v[44:45], v99 offset:54272
	ds_read_b64_tr_b16 v[48:49], v99 offset:54784
	ds_read_b64_tr_b16 v[46:47], v99 offset:53760
	v_permlane32_swap_b32_e32 v34, v36
	v_permlane32_swap_b32_e32 v35, v37
	v_permlane32_swap_b32_e32 v38, v40
	s_waitcnt lgkmcnt(2)
	v_mfma_f32_32x32x16_bf16 v[16:31], v[42:45], v[34:37], v[16:31]
	ds_read_b64_tr_b16 v[42:43], v99 offset:55296
	ds_read_b64_tr_b16 v[44:45], v99 offset:56320
	ds_read_b64_tr_b16 v[52:53], v99 offset:56832
	ds_read_b64_tr_b16 v[50:51], v99 offset:55808
	v_permlane32_swap_b32_e32 v39, v41
	s_waitcnt lgkmcnt(4)
	v_mfma_f32_32x32x16_bf16 v[0:15], v[46:49], v[34:37], v[0:15]
	s_waitcnt lgkmcnt(2)
	v_mfma_f32_32x32x16_bf16 v[16:31], v[42:45], v[38:41], v[16:31]
	s_waitcnt lgkmcnt(0)
	v_mfma_f32_32x32x16_bf16 v[0:15], v[50:53], v[38:41], v[0:15]
	v_cvt_pk_bf16_f32 v34, v81, v82
	v_cvt_pk_bf16_f32 v35, v83, v84
	v_cvt_pk_bf16_f32 v36, v85, v86
	v_cvt_pk_bf16_f32 v37, v54, v55
	v_cvt_pk_bf16_f32 v38, v87, v88
	v_cvt_pk_bf16_f32 v39, v89, v90
	v_cvt_pk_bf16_f32 v40, v91, v100
	v_cvt_pk_bf16_f32 v41, v101, v80
	ds_read_b64_tr_b16 v[42:43], v99 offset:57344
	ds_read_b64_tr_b16 v[44:45], v99 offset:58368
	ds_read_b64_tr_b16 v[48:49], v99 offset:58880
	ds_read_b64_tr_b16 v[46:47], v99 offset:57856
	v_permlane32_swap_b32_e32 v34, v36
	v_permlane32_swap_b32_e32 v35, v37
	v_permlane32_swap_b32_e32 v38, v40
	s_waitcnt lgkmcnt(2)
	v_mfma_f32_32x32x16_bf16 v[16:31], v[42:45], v[34:37], v[16:31]
	ds_read_b64_tr_b16 v[42:43], v99 offset:59392
	ds_read_b64_tr_b16 v[44:45], v99 offset:60416
	ds_read_b64_tr_b16 v[52:53], v99 offset:60928
	ds_read_b64_tr_b16 v[50:51], v99 offset:59904
	v_permlane32_swap_b32_e32 v39, v41
	s_waitcnt lgkmcnt(4)
	v_mfma_f32_32x32x16_bf16 v[0:15], v[46:49], v[34:37], v[0:15]
	s_waitcnt lgkmcnt(2)
	v_mfma_f32_32x32x16_bf16 v[16:31], v[42:45], v[38:41], v[16:31]
	s_waitcnt lgkmcnt(0)
	v_mfma_f32_32x32x16_bf16 v[0:15], v[50:53], v[38:41], v[0:15]
	v_cvt_pk_bf16_f32 v34, v102, v33
	v_cvt_pk_bf16_f32 v35, v103, v104
	v_cvt_pk_bf16_f32 v36, v105, v106
	v_cvt_pk_bf16_f32 v37, v107, v108
	v_cvt_pk_bf16_f32 v38, v109, v110
	v_cvt_pk_bf16_f32 v39, v111, v112
	v_cvt_pk_bf16_f32 v40, v113, v114
	v_cvt_pk_bf16_f32 v41, v115, v116
	ds_read_b64_tr_b16 v[42:43], v99 offset:61440
	ds_read_b64_tr_b16 v[44:45], v99 offset:62464
	ds_read_b64_tr_b16 v[48:49], v99 offset:62976
	ds_read_b64_tr_b16 v[46:47], v99 offset:61952
	v_permlane32_swap_b32_e32 v34, v36
	v_permlane32_swap_b32_e32 v35, v37
	v_permlane32_swap_b32_e32 v38, v40
	s_waitcnt lgkmcnt(2)
	v_mfma_f32_32x32x16_bf16 v[16:31], v[42:45], v[34:37], v[16:31]
	ds_read_b64_tr_b16 v[42:43], v99 offset:63488
	ds_read_b64_tr_b16 v[44:45], v99 offset:64512
	ds_read_b64_tr_b16 v[52:53], v99 offset:65024
	ds_read_b64_tr_b16 v[50:51], v99 offset:64000
	v_permlane32_swap_b32_e32 v39, v41
	s_waitcnt lgkmcnt(4)
	v_mfma_f32_32x32x16_bf16 v[0:15], v[46:49], v[34:37], v[0:15]
	s_waitcnt lgkmcnt(2)
	v_mfma_f32_32x32x16_bf16 v[16:31], v[42:45], v[38:41], v[16:31]
	s_waitcnt lgkmcnt(0)
	v_mfma_f32_32x32x16_bf16 v[0:15], v[50:53], v[38:41], v[0:15]
	v_cvt_pk_bf16_f32 v34, v117, v118
	v_cvt_pk_bf16_f32 v35, v119, v120
	v_cvt_pk_bf16_f32 v36, v121, v122
	v_cvt_pk_bf16_f32 v37, v123, v124
	v_cvt_pk_bf16_f32 v38, v125, v126
	v_cvt_pk_bf16_f32 v39, v127, v128
	v_cvt_pk_bf16_f32 v40, v129, v130
	v_cvt_pk_bf16_f32 v41, v131, v132
	ds_read_b64_tr_b16 v[42:43], v73 offset:16384
	ds_read_b64_tr_b16 v[44:45], v73 offset:17408
	ds_read_b64_tr_b16 v[48:49], v73 offset:17920
	ds_read_b64_tr_b16 v[46:47], v73 offset:16896
	v_permlane32_swap_b32_e32 v34, v36
	v_permlane32_swap_b32_e32 v35, v37
	v_permlane32_swap_b32_e32 v38, v40
	s_waitcnt lgkmcnt(2)
	v_mfma_f32_32x32x16_bf16 v[16:31], v[42:45], v[34:37], v[16:31]
	ds_read_b64_tr_b16 v[42:43], v73 offset:18432
	ds_read_b64_tr_b16 v[44:45], v73 offset:19456
	ds_read_b64_tr_b16 v[52:53], v73 offset:19968
	ds_read_b64_tr_b16 v[50:51], v73 offset:18944
	v_permlane32_swap_b32_e32 v39, v41
	s_waitcnt lgkmcnt(4)
	v_mfma_f32_32x32x16_bf16 v[0:15], v[46:49], v[34:37], v[0:15]
	s_waitcnt lgkmcnt(2)
	v_mfma_f32_32x32x16_bf16 v[16:31], v[42:45], v[38:41], v[16:31]
	s_waitcnt lgkmcnt(0)
	v_mfma_f32_32x32x16_bf16 v[0:15], v[50:53], v[38:41], v[0:15]
	v_add_f32_e32 v33, v133, v72
	v_cmp_gt_u32_e32 vcc, 32, v98
	s_and_saveexec_b64 s[2:3], vcc
	s_cbranch_execz .LBB0_857
	v_log_f32_e32 v34, v33
	s_lshl_b64 s[4:5], s[14:15], 20
	s_add_u32 s4, s13, s4
	s_addc_u32 s5, s38, s5
	v_add_f32_e32 v32, v32, v34
	v_lshlrev_b64 v[34:35], 5, v[94:95]
	v_lshl_add_u64 v[34:35], s[4:5], 0, v[34:35]
	s_lshl_b32 s8, s48, 2
	v_mul_f32_e32 v32, 0x3f317218, v32
	v_lshl_add_u64 v[34:35], v[34:35], 0, s[8:9]
	global_store_dword v[34:35], v32, off
	s_branch .LBB0_857

; __device__ __forceinline__ int opaque_tid() { int t = threadIdx.x; asm volatile("" : "+v"(t)); return t; }
; template <int NPE, int LDQ, int LDK, int VOFF, int LDO> ...
;   const int tid = opaque_tid(), wid = tid >> 6, lane = tid & 63, r32 = lane & 31, hi = lane >> 5;
;   unsigned vof[2], kof[2], pof;
; #pragma unroll
;   for (int j = 0; j < 2; ++j) { const int sp = 2 * wid + j;
;     { const int st = 2 * sp + (lane >> 5), kk = (st >> 2) * 8 + ((lane & 31) >> 2), k = (kk & ~0xC) | ((kk & 4) << 1) | ((kk & 8) >> 1), c = (st & 3) * 32 + (lane & 3) * 8;
;       vof[j] = (unsigned)(k * LDK + VOFF + c) * 2u; }
;     { const int row = 4 * sp + (lane >> 4), ch = (lane & 15) ^ (row & 7); kof[j] = (unsigned)(row * LDK + ch * 8) * 2u; } }
;   { const int row = 8 * wid + (lane >> 3), ch = (lane & 7) ^ ((row >> 1) & 7); pof = (unsigned)(row * 64 + ch * 8) * 2u; }
;     ...
;   char* s_prev = lds; char* s_cur = lds + R_STG; char* s_next = lds + 2 * R_STG;
;   ISSUE(0, s_prev); ISSUE(KVBLK, s_cur);
;   float m_reg = -1e30f, l_reg = 0; f32x16 o[4] = {}; bf16x8 qr[8 + NPE];
;   const bf16* Qw = (const bf16*)((const char*)Qb + (unsigned)((wid * QBLK + r32) * LDQ + hi * 8) * 2u);
; #pragma unroll
;   for (int d0 = 0; d0 < 8; ++d0) qr[d0] = *reinterpret_cast<const bf16x8*>(Qw + d0 * 16);
.LBB0_927:
	s_lshl_b32 s0, s10, 2
	s_ashr_i32 s1, s10, 7
	s_and_b32 s0, s0, 28
	s_and_b32 s2, s1, -2
	s_add_i32 s0, s0, s2
	s_ashr_i32 s2, s10, 3
	s_ashr_i32 s66, s0, 2
	s_bfe_u32 s30, s2, 0x10004
	s_ashr_i32 s67, s66, 31
	s_lshl_b32 s2, s2, 8
	s_lshl_b64 s[58:59], s[66:67], 12
	s_and_b32 s2, s2, 0xf00
	s_or_b32 s58, s58, s2
	s_and_b32 s0, s1, 2
	s_mul_i32 s2, s59, 0x600
	s_mul_hi_u32 s3, s58, 0x600
	s_or_b32 s0, s30, s0
	s_add_i32 s3, s3, s2
	s_mul_i32 s2, s58, 0x600
	s_add_u32 s2, s84, s2
	s_addc_u32 s3, s85, s3
	s_mul_i32 s31, s0, 0x180
	s_add_u32 s64, s2, s31
	s_addc_u32 s65, s3, 0
	s_lshl_b64 s[2:3], s[66:67], 23
	s_add_u32 s31, s82, s2
	v_mov_b32_e32 v16, v242
	s_addc_u32 s61, s83, s3
	s_lshl_b32 s62, s0, 9
	s_add_u32 s62, s31, s62
	v_ashrrev_i32_e32 v19, 6, v16
	v_lshlrev_b32_e32 v0, 3, v19
	v_bfe_u32 v1, v16, 2, 3
	s_mov_b32 s31, 0x1ffff3
	v_lshrrev_b32_e32 v2, 1, v16
	v_lshlrev_b32_e32 v3, 2, v19
	v_bitop3_b32 v1, v0, s31, v1 bitop3:0xc8
	v_and_b32_e32 v2, 8, v2
	v_and_b32_e32 v3, 4, v3
	v_or3_b32 v1, v1, v2, v3
	s_addc_u32 s63, s61, 0
	s_lshl_b64 s[76:77], s[66:67], 19
	v_lshlrev_b32_e32 v52, 11, v1
	v_bfe_u32 v1, v16, 4, 2
	v_lshlrev_b32_e32 v4, 14, v19
	s_add_u32 s70, s13, s76
	v_and_b32_e32 v18, 31, v16
	v_and_b32_e32 v2, 15, v16
	v_and_b32_e32 v243, 8, v0
	v_or_b32_e32 v243, v243, v1
	v_bitop3_b32 v3, v243, v16, 15 bitop3:0x78
	v_lshl_or_b32 v51, v1, 11, v4
	v_or3_b32 v1, v1, v0, 4
	s_addc_u32 s71, s21, s77
	s_lshl_b64 s[68:69], s[58:59], 7
	v_bfe_u32 v34, v16, 5, 1
	v_bitop3_b32 v2, v1, v2, 15 bitop3:0x6c
	v_lshl_or_b32 v146, v19, 5, v18
	s_add_u32 s66, s86, s68
	v_lshlrev_b32_e32 v54, 4, v2
	v_mul_lo_u32 v2, v146, s90
	v_lshlrev_b32_e32 v151, 3, v34
	s_addc_u32 s67, s87, s69
	v_or_b32_e32 v2, v2, v151
	s_add_u32 s68, s88, s68
	v_lshlrev_b32_e32 v38, 1, v2
	v_and_b32_e32 v2, 32, v16
	s_addc_u32 s69, s89, s69
	v_lshl_or_b32 v48, v3, 4, v51
	v_lshl_or_b32 v39, v146, 7, v2
	global_load_dwordx4 v[2:5], v38, s[64:65] offset:256
	global_load_dwordx4 v[6:9], v38, s[64:65] offset:320
	global_load_dwordx4 v[10:13], v39, s[68:69] offset:16
	global_load_dwordx4 v[20:23], v39, s[68:69]
	global_load_dwordx4 v[24:27], v39, s[66:67] offset:16
	global_load_dwordx4 v[28:31], v39, s[66:67]
	v_bfe_u32 v55, v16, 3, 3
	v_or_b32_e32 v32, v0, v55
	v_lshlrev_b32_e32 v17, 4, v16
	v_lshrrev_b32_e32 v0, 1, v32
	s_cmp_lg_u32 0, -1
	v_and_b32_e32 v50, 48, v17
	v_lshlrev_b32_e32 v53, 6, v34
	v_xor_b32_e32 v0, v0, v16
	v_lshlrev_b32_e32 v148, 11, v19
	s_cselect_b32 s31, 0, 0
	v_or3_b32 v144, v52, v50, v53
	v_lshlrev_b32_e32 v0, 4, v0
	v_add_u32_e32 v33, s31, v148
	v_lshl_or_b32 v37, v1, 11, v54
	v_and_b32_e32 v56, 0x70, v0
	v_lshl_add_u64 v[0:1], s[62:63], 0, v[144:145]
	s_mov_b64 s[72:73], 0x100
	v_readfirstlane_b32 s31, v33
	s_cmp_lg_u32 s93, -1
	v_lshl_add_u64 v[14:15], v[0:1], 0, s[72:73]
	s_mov_b32 m0, s31
	s_cselect_b32 s31, s93, 0
	global_load_lds_dwordx4 v[14:15], off
	v_add_u32_e32 v14, s31, v148
	v_add_u32_e32 v15, 0x400, v33
	v_readfirstlane_b32 s31, v14
	s_mov_b32 m0, s31
	v_readfirstlane_b32 s31, v15
	global_load_lds_dwordx4 v48, s[62:63]
	v_lshl_add_u64 v[0:1], v[0:1], 0, s[6:7]
	s_mov_b32 m0, s31
	s_cmp_lg_u32 s94, -1
	global_load_lds_dwordx4 v[0:1], off
	v_add_u32_e32 v0, 0x400, v14
	v_lshlrev_b32_e32 v150, 10, v19
	v_readfirstlane_b32 s31, v0
	s_mov_b32 m0, s31
	s_cselect_b32 s31, s94, 0
	v_add_u32_e32 v14, s31, v150
	v_or_b32_e32 v35, 0x100, v144
	v_readfirstlane_b32 s31, v14
	v_or_b32_e32 v36, 0x180, v144
	global_load_lds_dwordx4 v37, s[62:63]
	v_lshl_or_b32 v144, v32, 7, v56
	s_mov_b32 m0, s31
	v_lshl_add_u64 v[0:1], s[70:71], 0, v[144:145]
	global_load_lds_dwordx4 v144, s[70:71]
	s_add_u32 s70, s62, 0x20000
	s_addc_u32 s71, s63, 0
	s_cmp_lg_u32 s95, -1
	s_cselect_b32 s31, s95, 0
	v_add_u32_e32 v14, s31, v148
	s_cmp_lg_u32 s96, -1
	v_readfirstlane_b32 s31, v14
	s_mov_b32 m0, s31
	s_cselect_b32 s31, s96, 0
	v_add_u32_e32 v15, s31, v148
	v_add_u32_e32 v14, 0x400, v14
	v_readfirstlane_b32 s31, v15
	global_load_lds_dwordx4 v35, s[70:71]
	s_mov_b32 m0, s31
	v_readfirstlane_b32 s31, v14
	v_add_u32_e32 v14, 0x400, v15
	global_load_lds_dwordx4 v48, s[70:71]
	s_mov_b32 m0, s31
	v_readfirstlane_b32 s31, v14
	s_cmp_lg_u32 s97, -1
	global_load_lds_dwordx4 v36, s[70:71]
	s_mov_b32 m0, s31
	s_cselect_b32 s31, s97, 0
	v_add_u32_e32 v19, s31, v150
	global_load_lds_dwordx4 v37, s[70:71]
	v_readfirstlane_b32 s31, v19
	v_lshl_add_u64 v[14:15], v[0:1], 0, s[14:15]
	s_mov_b32 m0, s31
	s_waitcnt vmcnt(0)
; DI unsigned cvtpk(float lo, float hi) { unsigned r; asm volatile("v_cvt_pk_bf16_f32 %0, %1, %2" : "=v"(r) : "v"(lo), "v"(hi)); return r; }
; DI int v_rd_base(int lane) { return ((lane & 3) << 3) | (((lane >> 2) & 3) << 6) | (((lane >> 4) & 1) << 5) | (((lane >> 5) & 1) << 8); }
; #define RBAR() do { asm volatile("s_waitcnt vmcnt(0) lgkmcnt(0)" ::: "memory"); __builtin_amdgcn_s_barrier(); asm volatile("" ::: "memory"); } while (0)
; template <int NPE, int LDQ, int LDK, int VOFF, int LDO> ...
;     ...
;   ISSUE(0, s_prev); ISSUE(KVBLK, s_cur);
;   float m_reg = -1e30f, l_reg = 0; f32x16 o[4] = {}; bf16x8 qr[8 + NPE];
;   const bf16* Qw = (const bf16*)((const char*)Qb + (unsigned)((wid * QBLK + r32) * LDQ + hi * 8) * 2u);
; #pragma unroll
;   for (int d0 = 0; d0 < 8; ++d0) qr[d0] = *reinterpret_cast<const bf16x8*>(Qw + d0 * 16);
;   if constexpr (NPE > 0) {
;     const unsigned tqo = (unsigned)((wid * QBLK + r32) * 32 + hi * 8) * 4u;
; #pragma unroll
;     for (int d0 = 0; d0 < 2; ++d0) {
;       const u32x4 x1 = *reinterpret_cast<const u32x4*>(Qw + 128 + d0 * 16), x2 = *reinterpret_cast<const u32x4*>(Qw + 160 + d0 * 16);
;       const f32x4 cA = *(const f32x4*)((const char*)TCq + tqo + d0 * 64), cB = *(const f32x4*)((const char*)TCq + tqo + d0 * 64 + 16);
;       const f32x4 sA = *(const f32x4*)((const char*)TSq + tqo + d0 * 64), sB = *(const f32x4*)((const char*)TSq + tqo + d0 * 64 + 16);
;       u32x4 y1, y2;
; #pragma unroll
;       for (int e = 0; e < 4; ++e) {
;         const float a0 = __uint_as_float(x1[e] << 16), a1 = __uint_as_float(x1[e] & 0xffff0000u), b0 = __uint_as_float(x2[e] << 16), b1 = __uint_as_float(x2[e] & 0xffff0000u);
;         const float c0 = (e < 2) ? cA[2 * e] : cB[2 * e - 4], c1 = (e < 2) ? cA[2 * e + 1] : cB[2 * e - 3], s0 = (e < 2) ? sA[2 * e] : sB[2 * e - 4], s1 = (e < 2) ? sA[2 * e + 1] : sB[2 * e - 3];
;         y1[e] = cvtpk(a0 * c0 - b0 * s0, a1 * c1 - b1 * s1); y2[e] = cvtpk(b0 * c0 + a0 * s0, b1 * c1 + a1 * s1); }
;       qr[8 + d0] = *reinterpret_cast<bf16x8*>(&y1); qr[8 + d0 + 2] = *reinterpret_cast<bf16x8*>(&y2);
;     }
;   }
;     ...
;   f32x16 pA0, pA1, pB0, pB1; float mnA, mnB, alA, alB; bf16x8 pa0, pa1, pa2, pa3; const int NT = seq / KVBLK;
;   const int vlane = v_rd_base(lane);
;   RBAR();
	v_mov_b32_e32 v32, v20
	global_load_lds_dwordx4 v[14:15], off
	v_lshlrev_b32_e32 v15, 16, v2
	v_lshlrev_b32_e32 v14, 16, v6
	v_mov_b32_e32 v33, v28
	v_pk_mul_f32 v[32:33], v[32:33], v[14:15]
	global_load_dwordx4 v[136:139], v38, s[64:65]
	global_load_dwordx4 v[132:135], v38, s[64:65] offset:32
	global_load_dwordx4 v[128:131], v38, s[64:65] offset:64
	global_load_dwordx4 v[124:127], v38, s[64:65] offset:96
	global_load_dwordx4 v[120:123], v38, s[64:65] offset:128
	global_load_dwordx4 v[112:115], v38, s[64:65] offset:160
	global_load_dwordx4 v[108:111], v38, s[64:65] offset:192
	global_load_dwordx4 v[100:103], v38, s[64:65] offset:224
	v_sub_f32_e32 v19, v33, v32
	v_mov_b32_e32 v32, v28
	v_mov_b32_e32 v33, v20
	v_pk_mul_f32 v[14:15], v[32:33], v[14:15]
	v_mov_b32_e32 v28, v21
	v_add_f32_e32 v40, v14, v15
	v_and_b32_e32 v15, 0xffff0000, v2
	v_and_b32_e32 v14, 0xffff0000, v6
	v_pk_mul_f32 v[32:33], v[28:29], v[14:15]
	v_mov_b32_e32 v20, v29
	v_sub_f32_e32 v2, v33, v32
	v_pk_mul_f32 v[14:15], v[20:21], v[14:15]
	v_cvt_pk_bf16_f32 v104, v19, v2
	v_mov_b32_e32 v20, v22
	v_add_f32_e32 v2, v14, v15
	v_lshlrev_b32_e32 v15, 16, v3
	v_lshlrev_b32_e32 v14, 16, v7
	v_mov_b32_e32 v21, v30
	v_pk_mul_f32 v[20:21], v[20:21], v[14:15]
	v_cvt_pk_bf16_f32 v96, v40, v2
	v_and_b32_e32 v3, 0xffff0000, v3
	v_sub_f32_e32 v19, v21, v20
	v_mov_b32_e32 v20, v30
	v_mov_b32_e32 v21, v22
	v_and_b32_e32 v2, 0xffff0000, v7
	v_mov_b32_e32 v30, v23
	v_mov_b32_e32 v22, v31
	v_pk_mul_f32 v[6:7], v[30:31], v[2:3]
	v_pk_mul_f32 v[2:3], v[22:23], v[2:3]
	v_pk_mul_f32 v[14:15], v[20:21], v[14:15]
	v_sub_f32_e32 v6, v7, v6
	v_add_f32_e32 v2, v2, v3
	v_add_f32_e32 v14, v14, v15
	v_cvt_pk_bf16_f32 v105, v19, v6
	v_cvt_pk_bf16_f32 v97, v14, v2
	v_lshlrev_b32_e32 v3, 16, v4
	v_lshlrev_b32_e32 v2, 16, v8
	v_mov_b32_e32 v6, v10
	v_mov_b32_e32 v7, v24
	v_pk_mul_f32 v[6:7], v[6:7], v[2:3]
	s_add_u32 s62, s62, 0x40000
	v_sub_f32_e32 v14, v7, v6
	v_mov_b32_e32 v6, v24
	v_mov_b32_e32 v7, v10
	v_pk_mul_f32 v[2:3], v[6:7], v[2:3]
	v_mov_b32_e32 v24, v11
	v_add_f32_e32 v15, v2, v3
	v_and_b32_e32 v3, 0xffff0000, v4
	v_and_b32_e32 v2, 0xffff0000, v8
	v_mov_b32_e32 v10, v25
	v_pk_mul_f32 v[6:7], v[24:25], v[2:3]
	v_pk_mul_f32 v[2:3], v[10:11], v[2:3]
	v_sub_f32_e32 v4, v7, v6
	v_add_f32_e32 v2, v2, v3
	v_cvt_pk_bf16_f32 v106, v14, v4
	v_cvt_pk_bf16_f32 v98, v15, v2
	v_lshlrev_b32_e32 v3, 16, v5
	v_lshlrev_b32_e32 v2, 16, v9
	v_mov_b32_e32 v6, v12
	v_mov_b32_e32 v7, v26
	v_pk_mul_f32 v[6:7], v[6:7], v[2:3]
	s_addc_u32 s63, s63, 0
	v_sub_f32_e32 v8, v7, v6
	v_mov_b32_e32 v6, v26
	v_mov_b32_e32 v7, v12
	v_pk_mul_f32 v[2:3], v[6:7], v[2:3]
	v_mov_b32_e32 v26, v13
	v_add_f32_e32 v6, v2, v3
	v_and_b32_e32 v3, 0xffff0000, v5
	v_and_b32_e32 v2, 0xffff0000, v9
	v_mov_b32_e32 v12, v27
	v_pk_mul_f32 v[4:5], v[26:27], v[2:3]
	v_pk_mul_f32 v[2:3], v[12:13], v[2:3]
	v_sub_f32_e32 v4, v5, v4
	v_add_f32_e32 v2, v2, v3
	v_cvt_pk_bf16_f32 v107, v8, v4
	v_cvt_pk_bf16_f32 v99, v6, v2
	global_load_dwordx4 v[2:5], v38, s[64:65] offset:288
	global_load_dwordx4 v[6:9], v38, s[64:65] offset:352
	global_load_dwordx4 v[10:13], v39, s[68:69] offset:64
	global_load_dwordx4 v[20:23], v39, s[66:67] offset:64
	global_load_dwordx4 v[24:27], v39, s[68:69] offset:80
	global_load_dwordx4 v[28:31], v39, s[66:67] offset:80
	s_cmp_lg_u32 s11, -1
	s_cselect_b32 s31, s11, 0
	v_lshl_add_u64 v[0:1], v[0:1], 0, s[18:19]
	s_mov_b32 s61, s60
	s_mov_b32 s64, s60
	s_mov_b32 s65, s60
	s_mov_b32 s66, s60
	s_mov_b32 s67, s60
	s_mov_b32 s68, s60
	s_mov_b32 s69, s60
	s_mov_b32 s70, s60
	s_mov_b32 s71, s60
	s_mov_b32 s72, s60
	s_mov_b32 s73, s60
	s_mov_b32 s74, s60
	s_mov_b32 s75, s60
	v_mov_b32_e32 v49, v145
	v_mov_b32_e32 v161, 0
	s_waitcnt vmcnt(0)
	v_lshlrev_b32_e32 v15, 16, v2
	v_lshlrev_b32_e32 v14, 16, v6
	v_mov_b32_e32 v32, v10
	v_mov_b32_e32 v33, v20
	v_pk_mul_f32 v[32:33], v[32:33], v[14:15]
	s_nop 0
	v_sub_f32_e32 v19, v33, v32
	v_mov_b32_e32 v32, v20
	v_mov_b32_e32 v33, v10
	v_pk_mul_f32 v[14:15], v[32:33], v[14:15]
	v_mov_b32_e32 v20, v11
	v_add_f32_e32 v38, v14, v15
	v_and_b32_e32 v15, 0xffff0000, v2
	v_and_b32_e32 v14, 0xffff0000, v6
	v_pk_mul_f32 v[32:33], v[20:21], v[14:15]
	v_mov_b32_e32 v10, v21
	v_sub_f32_e32 v2, v33, v32
	v_pk_mul_f32 v[10:11], v[10:11], v[14:15]
	v_cvt_pk_bf16_f32 v140, v19, v2
	v_mov_b32_e32 v14, v12
	v_add_f32_e32 v2, v10, v11
	v_lshlrev_b32_e32 v11, 16, v3
	v_lshlrev_b32_e32 v10, 16, v7
	v_mov_b32_e32 v15, v22
	v_pk_mul_f32 v[14:15], v[14:15], v[10:11]
	v_cvt_pk_bf16_f32 v116, v38, v2
	v_and_b32_e32 v3, 0xffff0000, v3
	v_sub_f32_e32 v19, v15, v14
	v_mov_b32_e32 v14, v22
	v_mov_b32_e32 v15, v12
	v_and_b32_e32 v2, 0xffff0000, v7
	v_mov_b32_e32 v22, v13
	v_mov_b32_e32 v12, v23
	v_pk_mul_f32 v[6:7], v[22:23], v[2:3]
	v_pk_mul_f32 v[2:3], v[12:13], v[2:3]
	v_pk_mul_f32 v[10:11], v[14:15], v[10:11]
	v_sub_f32_e32 v6, v7, v6
	v_add_f32_e32 v2, v2, v3
	v_add_f32_e32 v10, v10, v11
	v_cvt_pk_bf16_f32 v141, v19, v6
	v_cvt_pk_bf16_f32 v117, v10, v2
	v_lshlrev_b32_e32 v3, 16, v4
	v_lshlrev_b32_e32 v2, 16, v8
	v_mov_b32_e32 v6, v24
	v_mov_b32_e32 v7, v28
	v_pk_mul_f32 v[6:7], v[6:7], v[2:3]
	v_lshlrev_b32_e32 v19, 4, v34
	v_sub_f32_e32 v10, v7, v6
	v_mov_b32_e32 v6, v28
	v_mov_b32_e32 v7, v24
	v_pk_mul_f32 v[2:3], v[6:7], v[2:3]
	v_mov_b32_e32 v28, v25
	v_add_f32_e32 v11, v2, v3
	v_and_b32_e32 v3, 0xffff0000, v4
	v_and_b32_e32 v2, 0xffff0000, v8
	v_mov_b32_e32 v24, v29
	v_pk_mul_f32 v[6:7], v[28:29], v[2:3]
	v_pk_mul_f32 v[2:3], v[24:25], v[2:3]
	v_sub_f32_e32 v4, v7, v6
	v_add_f32_e32 v2, v2, v3
	v_cvt_pk_bf16_f32 v142, v10, v4
	v_cvt_pk_bf16_f32 v118, v11, v2
	v_lshlrev_b32_e32 v3, 16, v5
	v_lshlrev_b32_e32 v2, 16, v9
	v_mov_b32_e32 v6, v26
	v_mov_b32_e32 v7, v30
	v_pk_mul_f32 v[6:7], v[6:7], v[2:3]
	v_lshlrev_b32_e32 v28, 8, v18
	v_sub_f32_e32 v8, v7, v6
	v_mov_b32_e32 v6, v30
	v_mov_b32_e32 v7, v26
	v_pk_mul_f32 v[2:3], v[6:7], v[2:3]
	v_mov_b32_e32 v30, v27
	v_add_f32_e32 v6, v2, v3
	v_and_b32_e32 v3, 0xffff0000, v5
	v_and_b32_e32 v2, 0xffff0000, v9
	v_mov_b32_e32 v26, v31
	v_pk_mul_f32 v[4:5], v[30:31], v[2:3]
	v_pk_mul_f32 v[2:3], v[26:27], v[2:3]
	v_sub_f32_e32 v4, v5, v4
	v_add_f32_e32 v2, v2, v3
	v_cvt_pk_bf16_f32 v143, v8, v4
	v_cvt_pk_bf16_f32 v119, v6, v2
	v_add_u32_e32 v2, s31, v148
	s_waitcnt vmcnt(0) lgkmcnt(0)
	s_barrier
; template <int NPE>
; DI void qkt_r(f32x16& p0, f32x16& p1, const char* Ks, const char* Ps, const bf16x8* qr, int r32, int hi) {
;   p0 = f32x16{}; p1 = f32x16{};
; #pragma unroll
;   for (int d0 = 0; d0 < 8; ++d0) { int cb = (d0 * 16 + hi * 8) * 2;
;     bf16x8 b0 = *reinterpret_cast<const bf16x8*>(Ks + KSWZ(r32, cb));
;     bf16x8 b1 = *reinterpret_cast<const bf16x8*>(Ks + KSWZ(32 + r32, cb));
;     p0 = __builtin_amdgcn_mfma_f32_32x32x16_bf16(b0, qr[d0], p0, 0, 0, 0);
;     p1 = __builtin_amdgcn_mfma_f32_32x32x16_bf16(b1, qr[d0], p1, 0, 0, 0); }
; #pragma unroll
;   for (int d0 = 0; d0 < NPE; ++d0) { int cb = (d0 * 16 + hi * 8) * 2;
;     bf16x8 b0 = *reinterpret_cast<const bf16x8*>(Ps + PSWZ(r32, cb));
;     bf16x8 b1 = *reinterpret_cast<const bf16x8*>(Ps + PSWZ(32 + r32, cb));
;     p0 = __builtin_amdgcn_mfma_f32_32x32x16_bf16(b0, qr[8 + d0], p0, 0, 0, 0);
;     p1 = __builtin_amdgcn_mfma_f32_32x32x16_bf16(b1, qr[8 + d0], p1, 0, 0, 0); }
	v_readfirstlane_b32 s31, v2
	s_mov_b32 m0, s31
	s_add_i32 s31, 0, 0x18000
	s_cmp_lg_u32 s31, -1
	s_cselect_b32 s31, s31, 0
	v_add_u32_e32 v3, s31, v148
	v_add_u32_e32 v2, 0x400, v2
	v_readfirstlane_b32 s31, v3
	global_load_lds_dwordx4 v35, s[62:63]
	s_mov_b32 m0, s31
	v_readfirstlane_b32 s31, v2
	v_add_u32_e32 v2, 0x400, v3
	global_load_lds_dwordx4 v48, s[62:63]
	s_mov_b32 m0, s31
	v_readfirstlane_b32 s31, v2
	global_load_lds_dwordx4 v36, s[62:63]
	s_mov_b32 m0, s31
	s_add_i32 s31, 0, 0x1c000
	s_cmp_lg_u32 s31, -1
	s_cselect_b32 s31, s31, 0
	v_add_u32_e32 v2, s31, v150
	v_and_b32_e32 v29, 0xf0, v17
	v_readfirstlane_b32 s31, v2
	global_load_lds_dwordx4 v37, s[62:63]
	s_mov_b32 m0, s31
	v_bitop3_b32 v188, v19, v28, v29 bitop3:0xde
	global_load_lds_dwordx4 v[0:1], off
	v_add_u32_e32 v187, 0, v188
	ds_read_b128 v[0:3], v187 offset:16384
	ds_read_b128 v[4:7], v187 offset:24576
	s_waitcnt lgkmcnt(0)
	v_mfma_f32_32x32x16_bf16 v[32:47], v[0:3], v[136:139], 0
	v_or_b32_e32 v30, 32, v19
	v_bitop3_b32 v191, v30, v28, v29 bitop3:0xde
	v_add_u32_e32 v189, 0, v191
	ds_read_b128 v[20:23], v189 offset:16384
	ds_read_b128 v[24:27], v189 offset:24576
	v_or_b32_e32 v31, 64, v19
	v_bitop3_b32 v194, v31, v28, v29 bitop3:0xde
	v_add_u32_e32 v190, 0, v194
	v_mfma_f32_32x32x16_bf16 v[0:15], v[4:7], v[136:139], 0
	v_or_b32_e32 v57, 0x60, v19
	v_bitop3_b32 v197, v57, v28, v29 bitop3:0xde
	v_add_u32_e32 v192, 0, v197
	v_and_b32_e32 v17, 0xc0, v17
	s_mov_b32 s62, s60
	s_mov_b32 s63, s60
	s_waitcnt lgkmcnt(0)
	v_mfma_f32_32x32x16_bf16 v[32:47], v[20:23], v[132:135], v[32:47]
	v_mfma_f32_32x32x16_bf16 v[0:15], v[24:27], v[132:135], v[0:15]
	ds_read_b128 v[20:23], v190 offset:16384
	ds_read_b128 v[24:27], v190 offset:24576
	s_waitcnt lgkmcnt(0)
	v_mfma_f32_32x32x16_bf16 v[32:47], v[20:23], v[128:131], v[32:47]
	v_mfma_f32_32x32x16_bf16 v[0:15], v[24:27], v[128:131], v[0:15]
	ds_read_b128 v[20:23], v192 offset:16384
	ds_read_b128 v[24:27], v192 offset:24576
	s_waitcnt lgkmcnt(0)
	v_mfma_f32_32x32x16_bf16 v[32:47], v[20:23], v[124:127], v[32:47]
	v_or_b32_e32 v20, 0x80, v19
	v_bitop3_b32 v200, v20, v28, v29 bitop3:0xde
	v_add_u32_e32 v193, 0, v200
	v_mfma_f32_32x32x16_bf16 v[0:15], v[24:27], v[124:127], v[0:15]
	ds_read_b128 v[20:23], v193 offset:16384
	ds_read_b128 v[24:27], v193 offset:24576
	s_waitcnt lgkmcnt(0)
	v_mfma_f32_32x32x16_bf16 v[32:47], v[20:23], v[120:123], v[32:47]
	v_or_b32_e32 v20, 0xa0, v19
	v_bitop3_b32 v203, v20, v28, v29 bitop3:0xde
	v_add_u32_e32 v195, 0, v203
	v_mfma_f32_32x32x16_bf16 v[0:15], v[24:27], v[120:123], v[0:15]
	ds_read_b128 v[20:23], v195 offset:16384
	ds_read_b128 v[24:27], v195 offset:24576
	s_waitcnt lgkmcnt(0)
	v_mfma_f32_32x32x16_bf16 v[32:47], v[20:23], v[112:115], v[32:47]
	v_or_b32_e32 v20, 0xc0, v19
	v_bitop3_b32 v205, v20, v28, v29 bitop3:0xde
	v_add_u32_e32 v196, 0, v205
	v_mfma_f32_32x32x16_bf16 v[0:15], v[24:27], v[112:115], v[0:15]
	ds_read_b128 v[20:23], v196 offset:16384
	ds_read_b128 v[24:27], v196 offset:24576
	s_waitcnt lgkmcnt(0)
	v_mfma_f32_32x32x16_bf16 v[32:47], v[20:23], v[108:111], v[32:47]
	v_or_b32_e32 v20, 0xe0, v19
	v_bitop3_b32 v206, v20, v28, v29 bitop3:0xde
	v_add_u32_e32 v198, 0, v206
	v_and_b32_e32 v28, 63, v16
	v_mfma_f32_32x32x16_bf16 v[0:15], v[24:27], v[108:111], v[0:15]
	ds_read_b128 v[20:23], v198 offset:16384
	ds_read_b128 v[24:27], v198 offset:24576
	s_waitcnt lgkmcnt(0)
	v_mfma_f32_32x32x16_bf16 v[32:47], v[20:23], v[100:103], v[32:47]
	v_mfma_f32_32x32x16_bf16 v[0:15], v[24:27], v[100:103], v[0:15]
	v_lshlrev_b32_e32 v26, 7, v18
	v_lshlrev_b32_e32 v18, 3, v16
	v_and_b32_e32 v27, 0x70, v18
	v_bitop3_b32 v207, v19, v26, v27 bitop3:0xde
	v_add_u32_e32 v199, 0, v207
	ds_read_b128 v[18:21], v199 offset:32768
	ds_read_b128 v[22:25], v199 offset:36864
	v_bitop3_b32 v208, v30, v26, v27 bitop3:0xde
	s_waitcnt lgkmcnt(0)
	v_mfma_f32_32x32x16_bf16 v[32:47], v[18:21], v[104:107], v[32:47]
	v_add_u32_e32 v201, 0, v208
	v_bitop3_b32 v209, v31, v26, v27 bitop3:0xde
	v_add_u32_e32 v202, 0, v209
	v_lshlrev_b32_e32 v16, 1, v16
	v_bitop3_b32 v210, v57, v26, v27 bitop3:0xde
	v_and_b32_e32 v16, 32, v16
	v_add_u32_e32 v204, 0, v210
	v_mfma_f32_32x32x16_bf16 v[0:15], v[22:25], v[104:107], v[0:15]
	ds_read_b128 v[18:21], v201 offset:32768
	ds_read_b128 v[22:25], v201 offset:36864
	ds_read_b128 v[58:61], v204 offset:36864
	s_waitcnt lgkmcnt(0)
	v_mfma_f32_32x32x16_bf16 v[32:47], v[18:21], v[140:143], v[32:47]
	ds_read_b128 v[18:21], v202 offset:32768
	v_mfma_f32_32x32x16_bf16 v[0:15], v[22:25], v[140:143], v[0:15]
	v_lshlrev_b32_e32 v22, 3, v28
	v_and_b32_e32 v28, 0x100, v22
	v_and_or_b32 v17, v22, 24, v17
	ds_read_b128 v[22:25], v202 offset:36864
	v_or3_b32 v147, v17, v16, v28
	s_waitcnt lgkmcnt(0)
	v_mfma_f32_32x32x16_bf16 v[32:47], v[18:21], v[96:99], v[32:47]
	ds_read_b128 v[16:19], v204 offset:32768
	v_mfma_f32_32x32x16_bf16 v[0:15], v[22:25], v[96:99], v[0:15]
	s_waitcnt lgkmcnt(0)
; DI void partialSM(f32x16& p0, f32x16& p1, float& m_reg, float& mn, float& alpha, const float SCALE) {
;   const float C = SCALE * 1.4426950408889634f;
;   float pmax = p0[0];
; #pragma unroll
;   for (int r = 1; r < 16; ++r) pmax = fmaxf(pmax, p0[r]);
; #pragma unroll
;   for (int r = 0; r < 16; ++r) pmax = fmaxf(pmax, p1[r]);
;   { auto rr = __builtin_amdgcn_permlane32_swap(__float_as_uint(pmax), __float_as_uint(pmax), false, false);
;     pmax = fmaxf(__uint_as_float(rr[0]), __uint_as_float(rr[1])); }
;   if (__builtin_expect(__all(pmax - m_reg <= THR / SCALE), 1)) { mn = m_reg; alpha = 1.f; }
;   else { mn = fmaxf(m_reg, pmax); alpha = __builtin_amdgcn_exp2f((m_reg - mn) * C); m_reg = mn; }
;   float mnC = -mn * C;
; #pragma unroll
;   for (int r = 0; r < 16; ++r) p0[r] = fmaf(p0[r], C, mnC);
; #pragma unroll
;   for (int r = 0; r < 16; ++r) p1[r] = fmaf(p1[r], C, mnC);
; #pragma unroll
;   for (int r = 0; r < 16; ++r) p0[r] = __builtin_amdgcn_exp2f(p0[r]);
; }
	v_mfma_f32_32x32x16_bf16 v[32:47], v[16:19], v[116:119], v[32:47]
	v_mov_b64_e32 v[16:17], s[60:61]
	v_mov_b64_e32 v[18:19], s[62:63]
	v_mov_b64_e32 v[20:21], s[64:65]
	v_mov_b64_e32 v[22:23], s[66:67]
	v_mov_b64_e32 v[24:25], s[68:69]
	v_mov_b64_e32 v[26:27], s[70:71]
	v_mov_b64_e32 v[28:29], s[72:73]
	v_mfma_f32_32x32x16_bf16 v[0:15], v[58:61], v[116:119], v[0:15]
	s_nop 3
	v_max_f32_e32 v57, v33, v33
	v_max_f32_e32 v58, v32, v32
	v_max_f32_e32 v57, v58, v57
	v_max3_f32 v57, v57, v34, v35
	v_max3_f32 v57, v57, v36, v37
	v_max3_f32 v57, v57, v38, v39
	v_max3_f32 v57, v57, v40, v41
	v_max3_f32 v57, v57, v42, v43
	v_max3_f32 v57, v57, v44, v45
	v_max3_f32 v57, v57, v46, v47
	v_max3_f32 v57, v57, v0, v1
	v_max3_f32 v57, v57, v2, v3
	v_max3_f32 v57, v57, v4, v5
	v_max3_f32 v57, v57, v6, v7
	v_max3_f32 v57, v57, v8, v9
	v_max3_f32 v57, v57, v10, v11
	v_max3_f32 v57, v57, v12, v13
	v_max3_f32 v57, v57, v14, v15
	v_mov_b32_e32 v58, v57
	s_nop 1
	v_permlane32_swap_b32_e32 v57, v58
	v_max_f32_e32 v58, v58, v58
	v_max_f32_e32 v57, v57, v57
	v_max_f32_e32 v57, v57, v58
	v_add_f32_e32 v58, 0x7149f2ca, v57
	v_max_f32_e32 v57, 0xf149f2ca, v57
	v_cmp_ge_f32_e32 vcc, s91, v58
	v_sub_f32_e32 v58, 0xf149f2ca, v57
	v_mul_f32_e32 v58, 0x3dd53b94, v58
	v_exp_f32_e32 v58, v58
	s_cmp_eq_u64 vcc, exec
	v_mov_b64_e32 v[30:31], s[74:75]
	s_cselect_b64 vcc, -1, 0
	s_add_u32 s62, s26, s76
	v_cndmask_b32_e32 v212, v57, v149, vcc
	s_addc_u32 s63, s27, s77
	s_lshl_b32 s1, s1, 9
	v_cndmask_b32_e64 v211, v58, 1.0, vcc
	v_mul_f32_e32 v58, 0xbdd53b94, v212
	s_lshl_b32 s30, s30, 9
	s_and_b32 s1, s1, 0x400
	v_mov_b32_e32 v57, v58
	s_or_b32 s1, s1, s30
	v_fmamk_f32 v32, v32, 0x3dd53b94, v58
	v_fmamk_f32 v33, v33, 0x3dd53b94, v58
	v_fmamk_f32 v34, v34, 0x3dd53b94, v58
	v_fmamk_f32 v35, v35, 0x3dd53b94, v58
	v_fmamk_f32 v36, v36, 0x3dd53b94, v58
	v_fmamk_f32 v37, v37, 0x3dd53b94, v58
	v_fmamk_f32 v38, v38, 0x3dd53b94, v58
	v_fmamk_f32 v39, v39, 0x3dd53b94, v58
	v_fmamk_f32 v40, v40, 0x3dd53b94, v58
	v_fmamk_f32 v41, v41, 0x3dd53b94, v58
	v_fmamk_f32 v42, v42, 0x3dd53b94, v58
	v_fmamk_f32 v43, v43, 0x3dd53b94, v58
	v_fmamk_f32 v44, v44, 0x3dd53b94, v58
	v_fmamk_f32 v45, v45, 0x3dd53b94, v58
	v_fmamk_f32 v46, v46, 0x3dd53b94, v58
	v_fmac_f32_e32 v57, 0x3dd53b94, v47
	v_pk_fma_f32 v[184:185], v[0:1], s[20:21], v[58:59] op_sel_hi:[1,0,0]
	v_lshlrev_b32_e32 v0, 7, v55
	s_or_b32 s1, s2, s1
	v_exp_f32_e32 v222, v32
	v_exp_f32_e32 v224, v33
	v_exp_f32_e32 v220, v34
	v_exp_f32_e32 v223, v35
	v_exp_f32_e32 v219, v36
	v_exp_f32_e32 v221, v37
	v_exp_f32_e32 v217, v38
	v_exp_f32_e32 v218, v39
	v_exp_f32_e32 v167, v40
	v_exp_f32_e32 v169, v41
	v_exp_f32_e32 v166, v42
	v_exp_f32_e32 v168, v43
	v_exp_f32_e32 v163, v44
	v_exp_f32_e32 v165, v45
	v_exp_f32_e32 v162, v46
	v_exp_f32_e32 v164, v57
	v_or3_b32 v144, v150, v0, v56
	s_add_u32 s2, s26, s1
	v_lshl_add_u64 v[152:153], s[62:63], 0, v[144:145]
	v_or3_b32 v144, v52, v53, v50
	s_addc_u32 s3, s27, s3
	v_pk_fma_f32 v[170:171], v[14:15], s[20:21], v[58:59] op_sel_hi:[1,0,0]
	v_pk_fma_f32 v[172:173], v[12:13], s[20:21], v[58:59] op_sel_hi:[1,0,0]
	v_pk_fma_f32 v[174:175], v[10:11], s[20:21], v[58:59] op_sel_hi:[1,0,0]
	v_pk_fma_f32 v[176:177], v[8:9], s[20:21], v[58:59] op_sel_hi:[1,0,0]
	v_pk_fma_f32 v[178:179], v[6:7], s[20:21], v[58:59] op_sel_hi:[1,0,0]
	v_pk_fma_f32 v[180:181], v[4:5], s[20:21], v[58:59] op_sel_hi:[1,0,0]
	v_pk_fma_f32 v[182:183], v[2:3], s[20:21], v[58:59] op_sel_hi:[1,0,0]
	v_lshl_add_u64 v[154:155], s[2:3], 0, v[144:145]
	v_lshl_add_u64 v[156:157], s[2:3], 0, v[48:49]
	v_or3_b32 v144, v51, v54, s92
	v_mov_b64_e32 v[62:63], v[30:31]
	v_mov_b64_e32 v[46:47], v[30:31]
	v_mov_b64_e32 v[0:1], v[16:17]
	v_lshl_add_u64 v[158:159], s[2:3], 0, v[144:145]
	v_mov_b64_e32 v[60:61], v[28:29]
	v_mov_b64_e32 v[58:59], v[26:27]
	v_mov_b64_e32 v[56:57], v[24:25]
	v_mov_b64_e32 v[54:55], v[22:23]
	v_mov_b64_e32 v[52:53], v[20:21]
	v_mov_b64_e32 v[50:51], v[18:19]
	v_mov_b64_e32 v[48:49], v[16:17]
	v_mov_b64_e32 v[44:45], v[28:29]
	v_mov_b64_e32 v[42:43], v[26:27]
	v_mov_b64_e32 v[40:41], v[24:25]
	v_mov_b64_e32 v[38:39], v[22:23]
	v_mov_b64_e32 v[36:37], v[20:21]
	v_mov_b64_e32 v[34:35], v[18:19]
	v_mov_b64_e32 v[32:33], v[16:17]
	v_mov_b64_e32 v[2:3], v[18:19]
	v_mov_b64_e32 v[4:5], v[20:21]
	v_mov_b64_e32 v[6:7], v[22:23]
	v_mov_b64_e32 v[8:9], v[24:25]
	v_mov_b64_e32 v[10:11], v[26:27]
	v_mov_b64_e32 v[12:13], v[28:29]
	v_mov_b64_e32 v[14:15], v[30:31]
	s_mov_b32 s2, 0
	s_mov_b32 s1, s95
	s_mov_b32 s62, s11
	s_mov_b32 s61, 1
; template <int NPE>
; DI void qkt_r(f32x16& p0, f32x16& p1, const char* Ks, const char* Ps, const bf16x8* qr, int r32, int hi) {
;   p0 = f32x16{}; p1 = f32x16{};
; #pragma unroll
;   for (int d0 = 0; d0 < 8; ++d0) { int cb = (d0 * 16 + hi * 8) * 2;
;     bf16x8 b0 = *reinterpret_cast<const bf16x8*>(Ks + KSWZ(r32, cb));
;     bf16x8 b1 = *reinterpret_cast<const bf16x8*>(Ks + KSWZ(32 + r32, cb));
;     p0 = __builtin_amdgcn_mfma_f32_32x32x16_bf16(b0, qr[d0], p0, 0, 0, 0);
;     p1 = __builtin_amdgcn_mfma_f32_32x32x16_bf16(b1, qr[d0], p1, 0, 0, 0); }
; #pragma unroll
;   for (int d0 = 0; d0 < NPE; ++d0) { int cb = (d0 * 16 + hi * 8) * 2;
;     bf16x8 b0 = *reinterpret_cast<const bf16x8*>(Ps + PSWZ(r32, cb));
;     bf16x8 b1 = *reinterpret_cast<const bf16x8*>(Ps + PSWZ(32 + r32, cb));
;     p0 = __builtin_amdgcn_mfma_f32_32x32x16_bf16(b0, qr[8 + d0], p0, 0, 0, 0);
;     p1 = __builtin_amdgcn_mfma_f32_32x32x16_bf16(b1, qr[8 + d0], p1, 0, 0, 0); }
.LBB0_928:
	s_mov_b32 s63, s1
	v_exp_f32_e32 v160, v185
	v_add_u32_e32 v68, s63, v188
	v_add_u32_e32 v243, s63, v191
	ds_read_b128 v[64:67], v68 offset:16384
	ds_read_b128 v[244:247], v243 offset:16384
	v_add_u32_e32 v252, s63, v194
	v_add_u32_e32 v253, s63, v197
	ds_read_b128 v[226:229], v252 offset:16384
	v_add_u32_e32 v144, s63, v200
	ds_read_b128 v[68:71], v68 offset:24576
	ds_read_b128 v[248:251], v243 offset:24576
	v_add_u32_e32 v243, s63, v203
	ds_read_b128 v[230:233], v252 offset:24576
	v_add_u32_e32 v252, s63, v205
	v_exp_f32_e32 v182, v182
	v_exp_f32_e32 v183, v183
	v_exp_f32_e32 v180, v180
	v_exp_f32_e32 v181, v181
	v_exp_f32_e32 v178, v178
	v_exp_f32_e32 v179, v179
	s_mov_b32 s1, s2
	v_exp_f32_e32 v185, v177
	v_cvt_pk_bf16_f32 v177, v162, v164
	v_exp_f32_e32 v215, v175
	v_cvt_pk_bf16_f32 v175, v166, v168
	v_exp_f32_e32 v186, v174
	v_exp_f32_e32 v216, v172
	v_exp_f32_e32 v225, v173
	v_cvt_pk_bf16_f32 v172, v219, v221
	v_cvt_pk_bf16_f32 v173, v217, v218
	s_waitcnt lgkmcnt(5)
	v_mfma_f32_32x32x16_bf16 v[80:95], v[64:67], v[136:139], 0
	v_cvt_pk_bf16_f32 v174, v167, v169
	v_permlane32_swap_b32_e32 v175, v177
	s_waitcnt lgkmcnt(4)
	v_mfma_f32_32x32x16_bf16 v[80:95], v[244:247], v[132:135], v[80:95]
	s_waitcnt lgkmcnt(3)
	v_mfma_f32_32x32x16_bf16 v[80:95], v[226:229], v[128:131], v[80:95]
	ds_read_b128 v[244:247], v253 offset:16384
	s_waitcnt lgkmcnt(3)
	v_mfma_f32_32x32x16_bf16 v[64:79], v[68:71], v[136:139], 0
	ds_read_b128 v[226:229], v144 offset:16384
	s_waitcnt lgkmcnt(3)
	v_mfma_f32_32x32x16_bf16 v[64:79], v[248:251], v[132:135], v[64:79]
	s_waitcnt lgkmcnt(2)
	v_mfma_f32_32x32x16_bf16 v[64:79], v[230:233], v[128:131], v[64:79]
	ds_read_b128 v[248:251], v253 offset:24576
	v_add_u32_e32 v253, s63, v206
	ds_read_b128 v[230:233], v144 offset:24576
	v_add_u32_e32 v144, s63, v207
	s_waitcnt lgkmcnt(3)
	v_mfma_f32_32x32x16_bf16 v[80:95], v[244:247], v[124:127], v[80:95]
	s_waitcnt lgkmcnt(2)
	v_mfma_f32_32x32x16_bf16 v[80:95], v[226:229], v[120:123], v[80:95]
	ds_read_b128 v[244:247], v243 offset:16384
	ds_read_b128 v[226:229], v252 offset:16384
	s_waitcnt lgkmcnt(3)
	v_mfma_f32_32x32x16_bf16 v[64:79], v[248:251], v[124:127], v[64:79]
	s_waitcnt lgkmcnt(2)
	v_mfma_f32_32x32x16_bf16 v[64:79], v[230:233], v[120:123], v[64:79]
	ds_read_b128 v[248:251], v243 offset:24576
	v_add_u32_e32 v243, s63, v208
	ds_read_b128 v[230:233], v252 offset:24576
	v_add_u32_e32 v252, s63, v209
	s_waitcnt lgkmcnt(3)
	v_mfma_f32_32x32x16_bf16 v[80:95], v[244:247], v[112:115], v[80:95]
	s_waitcnt lgkmcnt(2)
	v_mfma_f32_32x32x16_bf16 v[80:95], v[226:229], v[108:111], v[80:95]
	ds_read_b128 v[244:247], v253 offset:16384
	ds_read_b128 v[226:229], v144 offset:32768
	s_waitcnt lgkmcnt(3)
	v_mfma_f32_32x32x16_bf16 v[64:79], v[248:251], v[112:115], v[64:79]
	s_waitcnt lgkmcnt(2)
	v_mfma_f32_32x32x16_bf16 v[64:79], v[230:233], v[108:111], v[64:79]
	ds_read_b128 v[248:251], v253 offset:24576
	v_add_u32_e32 v253, s63, v210
	ds_read_b128 v[230:233], v144 offset:36864
	v_exp_f32_e32 v144, v184
	v_exp_f32_e32 v184, v176
	v_cvt_pk_bf16_f32 v176, v163, v165
	s_waitcnt lgkmcnt(3)
	v_mfma_f32_32x32x16_bf16 v[80:95], v[244:247], v[100:103], v[80:95]
	s_waitcnt lgkmcnt(2)
	v_mfma_f32_32x32x16_bf16 v[80:95], v[226:229], v[104:107], v[80:95]
	ds_read_b128 v[244:247], v243 offset:32768
	v_permlane32_swap_b32_e32 v174, v176
	ds_read_b128 v[226:229], v252 offset:32768
	s_waitcnt lgkmcnt(3)
	v_mfma_f32_32x32x16_bf16 v[64:79], v[248:251], v[100:103], v[64:79]
	s_waitcnt lgkmcnt(2)
	v_mfma_f32_32x32x16_bf16 v[64:79], v[230:233], v[104:107], v[64:79]
	ds_read_b128 v[248:251], v243 offset:36864
	v_add_u32_e32 v243, s1, v147
	ds_read_b128 v[230:233], v252 offset:36864
	s_waitcnt lgkmcnt(3)
	v_mfma_f32_32x32x16_bf16 v[80:95], v[244:247], v[140:143], v[80:95]
	s_waitcnt lgkmcnt(2)
	v_mfma_f32_32x32x16_bf16 v[80:95], v[226:229], v[96:99], v[80:95]
	ds_read_b128 v[244:247], v253 offset:32768
	v_exp_f32_e32 v226, v170
	v_add_f32_e32 v170, 0, v222
	v_exp_f32_e32 v227, v171
	v_add_f32_e32 v170, v224, v170
	v_cvt_pk_bf16_f32 v171, v220, v223
	v_add_f32_e32 v170, v220, v170
	s_waitcnt lgkmcnt(2)
	v_mfma_f32_32x32x16_bf16 v[64:79], v[248:251], v[140:143], v[64:79]
	v_add_f32_e32 v170, v223, v170
	v_permlane32_swap_b32_e32 v171, v173
	v_add_f32_e32 v170, v219, v170
	v_add_f32_e32 v170, v221, v170
	ds_read_b64_tr_b16 v[220:221], v243 offset:0x3000
	s_waitcnt lgkmcnt(2)
	v_mfma_f32_32x32x16_bf16 v[64:79], v[230:233], v[96:99], v[64:79]
	v_add_f32_e32 v170, v217, v170
	v_add_f32_e32 v170, v218, v170
	ds_read_b64_tr_b16 v[218:219], v243 offset:0x2800
	v_add_f32_e32 v170, v167, v170
	v_cvt_pk_bf16_f32 v167, v186, v215
	v_add_f32_e32 v170, v169, v170
	ds_read_b128 v[230:233], v253 offset:36864
	v_add_f32_e32 v170, v166, v170
	v_cvt_pk_bf16_f32 v166, v184, v185
	v_add_f32_e32 v170, v168, v170
	v_cvt_pk_bf16_f32 v168, v216, v225
	v_add_f32_e32 v170, v163, v170
	v_cvt_pk_bf16_f32 v163, v182, v183
	v_add_f32_e32 v170, v165, v170
	v_cvt_pk_bf16_f32 v165, v178, v179
	s_waitcnt lgkmcnt(3)
	v_mfma_f32_32x32x16_bf16 v[80:95], v[244:247], v[116:119], v[80:95]
	v_add_f32_e32 v170, v162, v170
	v_cvt_pk_bf16_f32 v162, v144, v160
	v_add_f32_e32 v170, v164, v170
	v_cvt_pk_bf16_f32 v164, v180, v181
	v_add_f32_e32 v170, v144, v170
	v_permlane32_swap_b32_e32 v163, v165
	v_add_f32_e32 v170, v160, v170
	v_permlane32_swap_b32_e32 v162, v164
	v_add_f32_e32 v170, v182, v170
	v_cvt_pk_bf16_f32 v169, v226, v227
	v_add_f32_e32 v170, v183, v170
	ds_read_b64_tr_b16 v[182:183], v243 offset:0x1000
	v_add_f32_e32 v170, v180, v170
	v_permlane32_swap_b32_e32 v166, v168
	v_add_f32_e32 v170, v181, v170
	ds_read_b64_tr_b16 v[180:181], v243 offset:0x800
	v_add_f32_e32 v170, v178, v170
	v_max_f32_e32 v252, v81, v81
	v_add_f32_e32 v170, v179, v170
	ds_read_b64_tr_b16 v[178:179], v243 offset:0
	v_add_f32_e32 v170, v184, v170
	v_max_f32_e32 v160, v80, v80
	v_add_f32_e32 v170, v185, v170
	ds_read_b64_tr_b16 v[184:185], v243 offset:0x1800
	v_add_f32_e32 v170, v186, v170
	v_max_f32_e32 v252, v160, v252
	v_add_f32_e32 v170, v215, v170
	v_max3_f32 v252, v252, v82, v83
	v_add_f32_e32 v170, v216, v170
	s_waitcnt lgkmcnt(4)
; #define SBAR() __builtin_amdgcn_sched_barrier(0)
; template <int OFF> DI s16x4 tr_read(int vb) {
;   s16x4 r; asm volatile("ds_read_b64_tr_b16 %0, %1 offset:%2" : "=&v"(r) : "v"(vb), "i"(OFF) : "memory"); return r;
; }
; template <int D0, bool SPLIT> DI void pv_one(f32x16& od, int vb, bf16x8 pa0, bf16x8 pa1, bf16x8 pa2, bf16x8 pa3) {
;     ...
;   if constexpr (SPLIT) {
;     { const s16x4 l0 = tr_read<v_rd_off(D0, 0, 0)>(vb), h0 = tr_read<v_rd_off(D0, 0, 1)>(vb), l1 = tr_read<v_rd_off(D0, 1, 0)>(vb), h1 = tr_read<v_rd_off(D0, 1, 1)>(vb);
;       asm volatile("s_waitcnt lgkmcnt(0)" ::: "memory"); SBAR();
;       od = __builtin_amdgcn_mfma_f32_32x32x16_bf16(PKV(l0, h0), pa0, od, 0, 0, 0);
;       od = __builtin_amdgcn_mfma_f32_32x32x16_bf16(PKV(l1, h1), pa1, od, 0, 0, 0); }
;     SBAR();
;     { const s16x4 l2 = tr_read<v_rd_off(D0, 2, 0)>(vb), h2 = tr_read<v_rd_off(D0, 2, 1)>(vb), l3 = tr_read<v_rd_off(D0, 3, 0)>(vb), h3 = tr_read<v_rd_off(D0, 3, 1)>(vb);
;       asm volatile("s_waitcnt lgkmcnt(0)" ::: "memory"); SBAR();
;       od = __builtin_amdgcn_mfma_f32_32x32x16_bf16(PKV(l2, h2), pa2, od, 0, 0, 0);
;       od = __builtin_amdgcn_mfma_f32_32x32x16_bf16(PKV(l3, h3), pa3, od, 0, 0, 0); }
;     SBAR();
;   } else {
;   const s16x4 l0 = tr_read<v_rd_off(D0, 0, 0)>(vb), h0 = tr_read<v_rd_off(D0, 0, 1)>(vb), l1 = tr_read<v_rd_off(D0, 1, 0)>(vb), h1 = tr_read<v_rd_off(D0, 1, 1)>(vb);
;   const s16x4 l2 = tr_read<v_rd_off(D0, 2, 0)>(vb), h2 = tr_read<v_rd_off(D0, 2, 1)>(vb), l3 = tr_read<v_rd_off(D0, 3, 0)>(vb), h3 = tr_read<v_rd_off(D0, 3, 1)>(vb);
;   asm volatile("s_waitcnt lgkmcnt(0)" ::: "memory"); SBAR();
;   od = __builtin_amdgcn_mfma_f32_32x32x16_bf16(PKV(l0, h0), pa0, od, 0, 0, 0);
;   od = __builtin_amdgcn_mfma_f32_32x32x16_bf16(PKV(l1, h1), pa1, od, 0, 0, 0);
;   od = __builtin_amdgcn_mfma_f32_32x32x16_bf16(PKV(l2, h2), pa2, od, 0, 0, 0);
;   od = __builtin_amdgcn_mfma_f32_32x32x16_bf16(PKV(l3, h3), pa3, od, 0, 0, 0);
;   }
; }
; template <bool SPLIT>
; DI void pv_d0(f32x16* o, int vb, bf16x8 pa0, bf16x8 pa1, bf16x8 pa2, bf16x8 pa3) {
;   pv_one<0, SPLIT>(o[0], vb, pa0, pa1, pa2, pa3); pv_one<1, SPLIT>(o[1], vb, pa0, pa1, pa2, pa3); pv_one<2, SPLIT>(o[2], vb, pa0, pa1, pa2, pa3); pv_one<3, SPLIT>(o[3], vb, pa0, pa1, pa2, pa3);
; }
	v_mfma_f32_32x32x16_bf16 v[64:79], v[230:233], v[116:119], v[64:79]
	ds_read_b64_tr_b16 v[216:217], v243 offset:0x2000
	v_add_f32_e32 v170, v225, v170
	v_max3_f32 v252, v252, v84, v85
	v_add_f32_e32 v170, v226, v170
	v_permlane32_swap_b32_e32 v167, v169
	v_add_f32_e32 v213, v227, v170
	v_cvt_pk_bf16_f32 v170, v222, v224
	ds_read_b64_tr_b16 v[222:223], v243 offset:0x3800
	ds_read_b64_tr_b16 v[224:225], v243 offset:0x3200
	ds_read_b64_tr_b16 v[226:227], v243 offset:0x3a00
	v_permlane32_swap_b32_e32 v170, v172
	v_max3_f32 v252, v252, v86, v87
	v_mov_b32_e32 v214, v213
	v_max3_f32 v252, v252, v88, v89
	v_max3_f32 v252, v252, v90, v91
	v_permlane32_swap_b32_e32 v213, v214
	v_max3_f32 v252, v252, v92, v93
	v_max3_f32 v252, v252, v94, v95
	v_max3_f32 v252, v252, v64, v65
	v_max3_f32 v252, v252, v66, v67
	v_max3_f32 v252, v252, v68, v69
	v_max3_f32 v252, v252, v70, v71
	s_waitcnt lgkmcnt(5)
	v_mfma_f32_32x32x16_bf16 v[16:31], v[178:181], v[170:173], v[16:31]
	v_max3_f32 v252, v252, v72, v73
	v_max3_f32 v252, v252, v74, v75
	v_max3_f32 v252, v252, v76, v77
	s_waitcnt lgkmcnt(4)
	v_mfma_f32_32x32x16_bf16 v[16:31], v[182:185], v[174:177], v[16:31]
	ds_read_b64_tr_b16 v[178:179], v243 offset:0x200
	ds_read_b64_tr_b16 v[180:181], v243 offset:0xa00
	v_max3_f32 v252, v252, v78, v79
	v_mov_b32_e32 v160, v252
	s_waitcnt lgkmcnt(5)
	v_mfma_f32_32x32x16_bf16 v[16:31], v[216:219], v[162:165], v[16:31]
	ds_read_b64_tr_b16 v[182:183], v243 offset:0x1200
	ds_read_b64_tr_b16 v[184:185], v243 offset:0x1a00
	v_permlane32_swap_b32_e32 v252, v160
	v_max_f32_e32 v160, v160, v160
	v_max_f32_e32 v252, v252, v252
	s_waitcnt lgkmcnt(6)
	v_mfma_f32_32x32x16_bf16 v[16:31], v[220:223], v[166:169], v[16:31]
	ds_read_b64_tr_b16 v[216:217], v243 offset:0x2200
	ds_read_b64_tr_b16 v[218:219], v243 offset:0x2a00
	v_max_f32_e32 v252, v252, v160
	v_max_f32_e32 v160, v212, v212
	v_max_f32_e32 v160, v160, v252
	ds_read_b64_tr_b16 v[220:221], v243 offset:0x3400
	ds_read_b64_tr_b16 v[222:223], v243 offset:0x3c00
	v_sub_f32_e32 v144, v212, v160
	v_mul_f32_e32 v144, 0x3dd53b94, v144
	v_exp_f32_e32 v144, v144
	s_waitcnt lgkmcnt(6)
	v_mfma_f32_32x32x16_bf16 v[48:63], v[178:181], v[170:173], v[48:63]
	s_waitcnt lgkmcnt(4)
	v_mfma_f32_32x32x16_bf16 v[48:63], v[182:185], v[174:177], v[48:63]
	ds_read_b64_tr_b16 v[178:179], v243 offset:0x400
	ds_read_b64_tr_b16 v[180:181], v243 offset:0xc00
	s_waitcnt lgkmcnt(4)
	v_mfma_f32_32x32x16_bf16 v[48:63], v[216:219], v[162:165], v[48:63]
	ds_read_b64_tr_b16 v[182:183], v243 offset:0x1400
	ds_read_b64_tr_b16 v[184:185], v243 offset:0x1c00
	v_mfma_f32_32x32x16_bf16 v[48:63], v[224:227], v[166:169], v[48:63]
	ds_read_b64_tr_b16 v[216:217], v243 offset:0x2400
	ds_read_b64_tr_b16 v[218:219], v243 offset:0x2c00
	ds_read_b64_tr_b16 v[224:225], v243 offset:0x3600
	ds_read_b64_tr_b16 v[226:227], v243 offset:0x3e00
	s_waitcnt lgkmcnt(6)
	v_mfma_f32_32x32x16_bf16 v[32:47], v[178:181], v[170:173], v[32:47]
	s_waitcnt lgkmcnt(4)
	v_mfma_f32_32x32x16_bf16 v[32:47], v[182:185], v[174:177], v[32:47]
	ds_read_b64_tr_b16 v[178:179], v243 offset:0x600
	ds_read_b64_tr_b16 v[180:181], v243 offset:0xe00
	s_waitcnt lgkmcnt(4)
	v_mfma_f32_32x32x16_bf16 v[32:47], v[216:219], v[162:165], v[32:47]
	ds_read_b64_tr_b16 v[182:183], v243 offset:0x1600
	ds_read_b64_tr_b16 v[184:185], v243 offset:0x1e00
	v_mfma_f32_32x32x16_bf16 v[32:47], v[220:223], v[166:169], v[32:47]
	ds_read_b64_tr_b16 v[216:217], v243 offset:0x2600
	ds_read_b64_tr_b16 v[218:219], v243 offset:0x2e00
	s_waitcnt lgkmcnt(4)
	v_mfma_f32_32x32x16_bf16 v[0:15], v[178:181], v[170:173], v[0:15]
	s_waitcnt lgkmcnt(2)
	v_mfma_f32_32x32x16_bf16 v[0:15], v[182:185], v[174:177], v[0:15]
	s_waitcnt lgkmcnt(0)
	v_mfma_f32_32x32x16_bf16 v[0:15], v[216:219], v[162:165], v[0:15]
	v_mfma_f32_32x32x16_bf16 v[0:15], v[224:227], v[166:169], v[0:15]
	v_sub_f32_e32 v162, v252, v212
	v_cmp_ge_f32_e32 vcc, s91, v162
	s_cmp_eq_u64 vcc, exec
	s_cselect_b64 s[2:3], -1, 0
	v_cndmask_b32_e64 v144, v144, 1.0, s[2:3]
	v_cmp_gt_f32_e32 vcc, 1.0, v144
	s_cbranch_vccz .LBB0_930
	v_pk_mul_f32 v[30:31], v[30:31], v[144:145] op_sel_hi:[1,0]
	v_pk_mul_f32 v[28:29], v[28:29], v[144:145] op_sel_hi:[1,0]
	v_pk_mul_f32 v[26:27], v[26:27], v[144:145] op_sel_hi:[1,0]
	v_pk_mul_f32 v[24:25], v[24:25], v[144:145] op_sel_hi:[1,0]
	v_pk_mul_f32 v[22:23], v[22:23], v[144:145] op_sel_hi:[1,0]
	v_pk_mul_f32 v[20:21], v[20:21], v[144:145] op_sel_hi:[1,0]
	v_pk_mul_f32 v[18:19], v[18:19], v[144:145] op_sel_hi:[1,0]
	v_pk_mul_f32 v[16:17], v[16:17], v[144:145] op_sel_hi:[1,0]
	v_pk_mul_f32 v[62:63], v[62:63], v[144:145] op_sel_hi:[1,0]
	v_pk_mul_f32 v[60:61], v[60:61], v[144:145] op_sel_hi:[1,0]
	v_pk_mul_f32 v[58:59], v[58:59], v[144:145] op_sel_hi:[1,0]
	v_pk_mul_f32 v[56:57], v[56:57], v[144:145] op_sel_hi:[1,0]
	v_pk_mul_f32 v[54:55], v[54:55], v[144:145] op_sel_hi:[1,0]
	v_pk_mul_f32 v[52:53], v[52:53], v[144:145] op_sel_hi:[1,0]
	v_pk_mul_f32 v[50:51], v[50:51], v[144:145] op_sel_hi:[1,0]
	v_pk_mul_f32 v[48:49], v[48:49], v[144:145] op_sel_hi:[1,0]
	v_pk_mul_f32 v[46:47], v[46:47], v[144:145] op_sel_hi:[1,0]
	v_pk_mul_f32 v[44:45], v[44:45], v[144:145] op_sel_hi:[1,0]
	v_pk_mul_f32 v[42:43], v[42:43], v[144:145] op_sel_hi:[1,0]
	v_pk_mul_f32 v[40:41], v[40:41], v[144:145] op_sel_hi:[1,0]
	v_pk_mul_f32 v[38:39], v[38:39], v[144:145] op_sel_hi:[1,0]
	v_pk_mul_f32 v[36:37], v[36:37], v[144:145] op_sel_hi:[1,0]
	v_pk_mul_f32 v[34:35], v[34:35], v[144:145] op_sel_hi:[1,0]
	v_pk_mul_f32 v[32:33], v[32:33], v[144:145] op_sel_hi:[1,0]
	v_pk_mul_f32 v[14:15], v[14:15], v[144:145] op_sel_hi:[1,0]
	v_pk_mul_f32 v[12:13], v[12:13], v[144:145] op_sel_hi:[1,0]
	v_pk_mul_f32 v[10:11], v[10:11], v[144:145] op_sel_hi:[1,0]
	v_pk_mul_f32 v[8:9], v[8:9], v[144:145] op_sel_hi:[1,0]
	v_pk_mul_f32 v[6:7], v[6:7], v[144:145] op_sel_hi:[1,0]
	v_pk_mul_f32 v[4:5], v[4:5], v[144:145] op_sel_hi:[1,0]
	v_pk_mul_f32 v[2:3], v[2:3], v[144:145] op_sel_hi:[1,0]
	v_pk_mul_f32 v[0:1], v[0:1], v[144:145] op_sel_hi:[1,0]
; DI void partialSM(f32x16& p0, f32x16& p1, float& m_reg, float& mn, float& alpha, const float SCALE) {
;   const float C = SCALE * 1.4426950408889634f;
;   float pmax = p0[0];
; #pragma unroll
;   for (int r = 1; r < 16; ++r) pmax = fmaxf(pmax, p0[r]);
; #pragma unroll
;   for (int r = 0; r < 16; ++r) pmax = fmaxf(pmax, p1[r]);
;   { auto rr = __builtin_amdgcn_permlane32_swap(__float_as_uint(pmax), __float_as_uint(pmax), false, false);
;     pmax = fmaxf(__uint_as_float(rr[0]), __uint_as_float(rr[1])); }
;   if (__builtin_expect(__all(pmax - m_reg <= THR / SCALE), 1)) { mn = m_reg; alpha = 1.f; }
;   else { mn = fmaxf(m_reg, pmax); alpha = __builtin_amdgcn_exp2f((m_reg - mn) * C); m_reg = mn; }
;   float mnC = -mn * C;
; #pragma unroll
;   for (int r = 0; r < 16; ++r) p0[r] = fmaf(p0[r], C, mnC);
; #pragma unroll
;   for (int r = 0; r < 16; ++r) p1[r] = fmaf(p1[r], C, mnC);
; #pragma unroll
;   for (int r = 0; r < 16; ++r) p0[r] = __builtin_amdgcn_exp2f(p0[r]);
; }
.LBB0_930:
	v_add_u32_e32 v168, s1, v148
	s_add_i32 s30, s1, 0x4000
	v_lshl_add_u64 v[162:163], v[154:155], 0, s[4:5]
	v_readfirstlane_b32 s31, v168
	v_add_u32_e32 v170, s30, v148
	v_lshl_add_u64 v[164:165], v[162:163], 0, s[38:39]
	v_readfirstlane_b32 s30, v170
	s_mov_b32 m0, s31
	s_waitcnt vmcnt(0) lgkmcnt(0)
	v_add_u32_e32 v168, 0x400, v168
	s_barrier
	global_load_lds_dwordx4 v[164:165], off
	v_lshl_add_u64 v[164:165], v[156:157], 0, s[4:5]
	s_mov_b32 m0, s30
	v_readfirstlane_b32 s30, v168
	v_lshl_add_u64 v[166:167], v[164:165], 0, s[40:41]
	v_add_u32_e32 v170, 0x400, v170
	global_load_lds_dwordx4 v[166:167], off
	s_mov_b32 m0, s30
	v_readfirstlane_b32 s30, v170
	v_lshl_add_u64 v[166:167], v[162:163], 0, s[42:43]
	v_add_u32_e32 v243, s62, v191
	global_load_lds_dwordx4 v[166:167], off
	v_lshl_add_u64 v[166:167], v[158:159], 0, s[4:5]
	s_mov_b32 m0, s30
	s_add_i32 s30, s1, 0x8000
	v_lshl_add_u64 v[168:169], v[166:167], 0, s[40:41]
	v_add_u32_e32 v172, s30, v150
	global_load_lds_dwordx4 v[168:169], off
	v_readfirstlane_b32 s30, v172
	v_lshl_add_u64 v[168:169], v[152:153], 0, s[4:5]
	ds_read_b128 v[176:179], v243 offset:24576
	v_lshl_add_u64 v[170:171], v[168:169], 0, s[44:45]
	s_mov_b32 m0, s30
	v_add_u32_e32 v252, s62, v194
	global_load_lds_dwordx4 v[170:171], off
	v_cndmask_b32_e64 v170, v160, v212, s[2:3]
	v_add_u32_e32 v253, s62, v197
	v_mul_f32_e32 v160, 0xbdd53b94, v170
	ds_read_b128 v[244:247], v243 offset:16384
	v_fmamk_f32 v80, v80, 0x3dd53b94, v160
	v_fmamk_f32 v81, v81, 0x3dd53b94, v160
	v_fmamk_f32 v82, v82, 0x3dd53b94, v160
	v_fmamk_f32 v83, v83, 0x3dd53b94, v160
	v_fmamk_f32 v183, v68, 0x3dd53b94, v160
	v_add_u32_e32 v68, s62, v188
	v_exp_f32_e32 v219, v80
	v_exp_f32_e32 v220, v81
	v_exp_f32_e32 v221, v82
	v_exp_f32_e32 v222, v83
	ds_read_b128 v[80:83], v68 offset:24576
	v_fmamk_f32 v84, v84, 0x3dd53b94, v160
	v_fmamk_f32 v85, v85, 0x3dd53b94, v160
	v_fmamk_f32 v86, v86, 0x3dd53b94, v160
	v_fmamk_f32 v87, v87, 0x3dd53b94, v160
	v_fmamk_f32 v88, v88, 0x3dd53b94, v160
	v_fmamk_f32 v89, v89, 0x3dd53b94, v160
	v_fmamk_f32 v90, v90, 0x3dd53b94, v160
	v_fmamk_f32 v91, v91, 0x3dd53b94, v160
	v_fmamk_f32 v92, v92, 0x3dd53b94, v160
	v_fmamk_f32 v93, v93, 0x3dd53b94, v160
	v_fmamk_f32 v94, v94, 0x3dd53b94, v160
	v_fmamk_f32 v95, v95, 0x3dd53b94, v160
	v_exp_f32_e32 v223, v84
	v_exp_f32_e32 v224, v85
	v_exp_f32_e32 v225, v86
	v_exp_f32_e32 v226, v87
	v_exp_f32_e32 v227, v88
	v_exp_f32_e32 v228, v89
	v_exp_f32_e32 v229, v90
	v_exp_f32_e32 v230, v91
	v_exp_f32_e32 v231, v92
	v_exp_f32_e32 v232, v93
	v_exp_f32_e32 v233, v94
	v_exp_f32_e32 v234, v95
	v_fmamk_f32 v171, v64, 0x3dd53b94, v160
	v_fmamk_f32 v180, v65, 0x3dd53b94, v160
	v_fmamk_f32 v181, v66, 0x3dd53b94, v160
	s_waitcnt lgkmcnt(0)
	v_mfma_f32_32x32x16_bf16 v[80:95], v[80:83], v[136:139], 0
	v_fmamk_f32 v182, v67, 0x3dd53b94, v160
	ds_read_b128 v[64:67], v68 offset:16384
	v_fmamk_f32 v184, v69, 0x3dd53b94, v160
	v_fmamk_f32 v185, v70, 0x3dd53b94, v160
	v_fmamk_f32 v186, v71, 0x3dd53b94, v160
	v_fmamk_f32 v212, v72, 0x3dd53b94, v160
	v_mfma_f32_32x32x16_bf16 v[80:95], v[176:179], v[132:135], v[80:95]
	v_fmamk_f32 v215, v73, 0x3dd53b94, v160
	v_fmamk_f32 v216, v74, 0x3dd53b94, v160
	v_fmamk_f32 v217, v75, 0x3dd53b94, v160
	v_fmamk_f32 v218, v76, 0x3dd53b94, v160
	v_fmamk_f32 v235, v77, 0x3dd53b94, v160
	v_fmamk_f32 v236, v78, 0x3dd53b94, v160
	ds_read_b128 v[176:179], v252 offset:24576
	v_fmac_f32_e32 v160, 0x3dd53b94, v79
	v_add_u32_e32 v243, s62, v203
	ds_read_b128 v[248:251], v252 offset:16384
	v_add_u32_e32 v252, s62, v205
	ds_read_b128 v[172:175], v253 offset:16384
	v_exp_f32_e32 v171, v171
	v_exp_f32_e32 v180, v180
	v_exp_f32_e32 v181, v181
	v_exp_f32_e32 v182, v182
	v_exp_f32_e32 v183, v183
	v_exp_f32_e32 v184, v184
	v_exp_f32_e32 v185, v185
	v_exp_f32_e32 v186, v186
	v_exp_f32_e32 v212, v212
	v_exp_f32_e32 v237, v215
	s_waitcnt lgkmcnt(3)
	v_mfma_f32_32x32x16_bf16 v[64:79], v[64:67], v[136:139], 0
	v_exp_f32_e32 v238, v216
	v_exp_f32_e32 v217, v217
	v_exp_f32_e32 v239, v218
	v_mfma_f32_32x32x16_bf16 v[64:79], v[244:247], v[132:135], v[64:79]
	v_exp_f32_e32 v235, v235
	v_exp_f32_e32 v236, v236
	v_exp_f32_e32 v160, v160
	s_waitcnt lgkmcnt(2)
	v_mfma_f32_32x32x16_bf16 v[80:95], v[176:179], v[128:131], v[80:95]
	v_cvt_pk_bf16_f32 v218, v212, v237
	s_waitcnt lgkmcnt(1)
	v_mfma_f32_32x32x16_bf16 v[64:79], v[248:251], v[128:131], v[64:79]
	ds_read_b128 v[176:179], v253 offset:24576
	v_add_u32_e32 v253, s62, v206
	s_waitcnt lgkmcnt(1)
	v_mfma_f32_32x32x16_bf16 v[64:79], v[172:175], v[124:127], v[64:79]
	ds_read_b128 v[248:251], v243 offset:16384
	ds_read_b128 v[172:175], v252 offset:16384
	s_waitcnt lgkmcnt(2)
	v_mfma_f32_32x32x16_bf16 v[80:95], v[176:179], v[124:127], v[80:95]
	v_add_u32_e32 v176, s62, v200
	ds_read_b128 v[244:247], v176 offset:16384
	ds_read_b128 v[176:179], v176 offset:24576
	s_waitcnt lgkmcnt(1)
	v_mfma_f32_32x32x16_bf16 v[64:79], v[244:247], v[120:123], v[64:79]
	s_waitcnt lgkmcnt(0)
	v_mfma_f32_32x32x16_bf16 v[80:95], v[176:179], v[120:123], v[80:95]
	ds_read_b128 v[244:247], v253 offset:16384
	v_mfma_f32_32x32x16_bf16 v[64:79], v[248:251], v[112:115], v[64:79]
	ds_read_b128 v[176:179], v243 offset:24576
	v_add_u32_e32 v243, s62, v208
	v_mfma_f32_32x32x16_bf16 v[64:79], v[172:175], v[108:111], v[64:79]
	ds_read_b128 v[172:175], v243 offset:32768
	s_waitcnt lgkmcnt(2)
	v_mfma_f32_32x32x16_bf16 v[64:79], v[244:247], v[100:103], v[64:79]
	s_waitcnt lgkmcnt(1)
	v_mfma_f32_32x32x16_bf16 v[80:95], v[176:179], v[112:115], v[80:95]
	ds_read_b128 v[176:179], v252 offset:24576
	v_add_u32_e32 v252, s62, v209
	ds_read_b128 v[244:247], v252 offset:32768
	s_waitcnt lgkmcnt(1)
; DI void finishSM(f32x16& p0, f32x16& p1, float alpha, float& l_reg, bf16x8& pa0, bf16x8& pa1, bf16x8& pa2, bf16x8& pa3) {
; #pragma unroll
;   for (int r = 0; r < 16; ++r) p1[r] = __builtin_amdgcn_exp2f(p1[r]);
;   float ps = 0;
; #pragma unroll
;   for (int r = 0; r < 16; ++r) ps += p0[r];
; #pragma unroll
;   for (int r = 0; r < 16; ++r) ps += p1[r];
;   { auto rr = __builtin_amdgcn_permlane32_swap(__float_as_uint(ps), __float_as_uint(ps), false, false);
;     ps = __uint_as_float(rr[0]) + __uint_as_float(rr[1]); }
;   l_reg = l_reg * alpha + ps;
;   PK4(p0, 0, pa0); PK4(p0, 8, pa1); PK4(p1, 0, pa2); PK4(p1, 8, pa3);
; }
; template <int OFF> DI s16x4 tr_read(int vb) {
;   s16x4 r; asm volatile("ds_read_b64_tr_b16 %0, %1 offset:%2" : "=&v"(r) : "v"(vb), "i"(OFF) : "memory"); return r;
; }
; template <int D0, bool SPLIT> DI void pv_one(f32x16& od, int vb, bf16x8 pa0, bf16x8 pa1, bf16x8 pa2, bf16x8 pa3) {
;     ...
;   if constexpr (SPLIT) {
;     { const s16x4 l0 = tr_read<v_rd_off(D0, 0, 0)>(vb), h0 = tr_read<v_rd_off(D0, 0, 1)>(vb), l1 = tr_read<v_rd_off(D0, 1, 0)>(vb), h1 = tr_read<v_rd_off(D0, 1, 1)>(vb);
;       asm volatile("s_waitcnt lgkmcnt(0)" ::: "memory"); SBAR();
;       od = __builtin_amdgcn_mfma_f32_32x32x16_bf16(PKV(l0, h0), pa0, od, 0, 0, 0);
;       od = __builtin_amdgcn_mfma_f32_32x32x16_bf16(PKV(l1, h1), pa1, od, 0, 0, 0); }
;     SBAR();
;     { const s16x4 l2 = tr_read<v_rd_off(D0, 2, 0)>(vb), h2 = tr_read<v_rd_off(D0, 2, 1)>(vb), l3 = tr_read<v_rd_off(D0, 3, 0)>(vb), h3 = tr_read<v_rd_off(D0, 3, 1)>(vb);
;       asm volatile("s_waitcnt lgkmcnt(0)" ::: "memory"); SBAR();
;       od = __builtin_amdgcn_mfma_f32_32x32x16_bf16(PKV(l2, h2), pa2, od, 0, 0, 0);
;       od = __builtin_amdgcn_mfma_f32_32x32x16_bf16(PKV(l3, h3), pa3, od, 0, 0, 0); }
;     SBAR();
;   } else {
;   const s16x4 l0 = tr_read<v_rd_off(D0, 0, 0)>(vb), h0 = tr_read<v_rd_off(D0, 0, 1)>(vb), l1 = tr_read<v_rd_off(D0, 1, 0)>(vb), h1 = tr_read<v_rd_off(D0, 1, 1)>(vb);
;   const s16x4 l2 = tr_read<v_rd_off(D0, 2, 0)>(vb), h2 = tr_read<v_rd_off(D0, 2, 1)>(vb), l3 = tr_read<v_rd_off(D0, 3, 0)>(vb), h3 = tr_read<v_rd_off(D0, 3, 1)>(vb);
;   asm volatile("s_waitcnt lgkmcnt(0)" ::: "memory"); SBAR();
;   od = __builtin_amdgcn_mfma_f32_32x32x16_bf16(PKV(l0, h0), pa0, od, 0, 0, 0);
;   od = __builtin_amdgcn_mfma_f32_32x32x16_bf16(PKV(l1, h1), pa1, od, 0, 0, 0);
	v_mfma_f32_32x32x16_bf16 v[80:95], v[176:179], v[108:111], v[80:95]
	ds_read_b128 v[176:179], v253 offset:24576
	v_add_u32_e32 v253, s62, v210
	s_waitcnt lgkmcnt(0)
	v_mfma_f32_32x32x16_bf16 v[80:95], v[176:179], v[100:103], v[80:95]
	v_add_u32_e32 v176, s62, v207
	ds_read_b128 v[248:251], v176 offset:32768
	ds_read_b128 v[176:179], v176 offset:36864
	s_waitcnt lgkmcnt(1)
	v_mfma_f32_32x32x16_bf16 v[64:79], v[248:251], v[104:107], v[64:79]
	s_waitcnt lgkmcnt(0)
	v_mfma_f32_32x32x16_bf16 v[80:95], v[176:179], v[104:107], v[80:95]
	ds_read_b128 v[248:251], v253 offset:32768
	v_mfma_f32_32x32x16_bf16 v[64:79], v[172:175], v[140:143], v[64:79]
	ds_read_b128 v[176:179], v243 offset:36864
	v_mfma_f32_32x32x16_bf16 v[64:79], v[244:247], v[96:99], v[64:79]
	v_add_f32_e32 v172, 0, v219
	v_cvt_pk_bf16_f32 v173, v221, v222
	v_add_f32_e32 v172, v220, v172
	v_cvt_pk_bf16_f32 v174, v223, v224
	v_add_f32_e32 v172, v221, v172
	v_cvt_pk_bf16_f32 v221, v236, v160
	v_add_f32_e32 v172, v222, v172
	v_cvt_pk_bf16_f32 v175, v225, v226
	v_add_f32_e32 v172, v223, v172
	v_add_f32_e32 v172, v224, v172
	v_permlane32_swap_b32_e32 v173, v175
	v_add_f32_e32 v172, v225, v172
	v_add_f32_e32 v172, v226, v172
	v_add_f32_e32 v172, v227, v172
	v_add_f32_e32 v172, v228, v172
	v_add_f32_e32 v172, v229, v172
	v_add_f32_e32 v172, v230, v172
	s_waitcnt lgkmcnt(1)
	v_mfma_f32_32x32x16_bf16 v[64:79], v[248:251], v[116:119], v[64:79]
	v_add_f32_e32 v172, v231, v172
	v_add_f32_e32 v172, v232, v172
	v_add_f32_e32 v172, v233, v172
	s_waitcnt lgkmcnt(0)
	v_mfma_f32_32x32x16_bf16 v[80:95], v[176:179], v[140:143], v[80:95]
	v_add_f32_e32 v172, v234, v172
	v_add_f32_e32 v172, v171, v172
	v_add_f32_e32 v172, v180, v172
	v_cvt_pk_bf16_f32 v180, v171, v180
	ds_read_b128 v[176:179], v252 offset:36864
	v_add_f32_e32 v172, v181, v172
	v_cvt_pk_bf16_f32 v181, v181, v182
	v_add_f32_e32 v172, v182, v172
	v_cvt_pk_bf16_f32 v182, v183, v184
	v_add_f32_e32 v172, v183, v172
	v_cvt_pk_bf16_f32 v183, v185, v186
	v_add_f32_e32 v172, v184, v172
	v_permlane32_swap_b32_e32 v180, v182
	v_add_f32_e32 v172, v185, v172
	v_permlane32_swap_b32_e32 v181, v183
	v_add_f32_e32 v172, v186, v172
	v_max_f32_e32 v171, v64, v64
	v_add_f32_e32 v172, v212, v172
	v_add_f32_e32 v172, v237, v172
	v_add_f32_e32 v172, v238, v172
	v_add_f32_e32 v172, v217, v172
	v_add_f32_e32 v172, v239, v172
	v_add_f32_e32 v172, v235, v172
	v_add_f32_e32 v172, v236, v172
	v_add_f32_e32 v215, v160, v172
	v_add_u32_e32 v160, s63, v147
	v_cvt_pk_bf16_f32 v172, v219, v220
	ds_read_b64_tr_b16 v[222:223], v160 offset:0
	ds_read_b64_tr_b16 v[224:225], v160 offset:0x800
	v_cvt_pk_bf16_f32 v219, v238, v217
	v_permlane32_swap_b32_e32 v172, v174
	v_cvt_pk_bf16_f32 v220, v239, v235
	ds_read_b64_tr_b16 v[236:237], v160 offset:0x3800
	ds_read_b64_tr_b16 v[238:239], v160 offset:0x3200
	ds_read_b64_tr_b16 v[240:241], v160 offset:0x3a00
	v_permlane32_swap_b32_e32 v218, v220
	v_permlane32_swap_b32_e32 v219, v221
	s_waitcnt lgkmcnt(5)
	v_mfma_f32_32x32x16_bf16 v[80:95], v[176:179], v[96:99], v[80:95]
	v_mov_b32_e32 v216, v215
	ds_read_b128 v[176:179], v253 offset:36864
	s_waitcnt lgkmcnt(4)
	v_mfma_f32_32x32x16_bf16 v[16:31], v[222:225], v[172:175], v[16:31]
	v_permlane32_swap_b32_e32 v215, v216
	ds_read_b64_tr_b16 v[222:223], v160 offset:0x200
	ds_read_b64_tr_b16 v[224:225], v160 offset:0xa00
	s_waitcnt lgkmcnt(2)
	v_mfma_f32_32x32x16_bf16 v[80:95], v[176:179], v[116:119], v[80:95]
	v_cvt_pk_bf16_f32 v176, v227, v228
	v_cvt_pk_bf16_f32 v177, v229, v230
	ds_read_b64_tr_b16 v[226:227], v160 offset:0x1000
	ds_read_b64_tr_b16 v[228:229], v160 offset:0x1800
	v_cvt_pk_bf16_f32 v178, v231, v232
	v_cvt_pk_bf16_f32 v179, v233, v234
	ds_read_b64_tr_b16 v[230:231], v160 offset:0x2000
	ds_read_b64_tr_b16 v[232:233], v160 offset:0x2800
	v_permlane32_swap_b32_e32 v176, v178
	v_permlane32_swap_b32_e32 v177, v179
	ds_read_b64_tr_b16 v[234:235], v160 offset:0x3000
	s_waitcnt lgkmcnt(5)
	v_mfma_f32_32x32x16_bf16 v[48:63], v[222:225], v[172:175], v[48:63]
	ds_read_b64_tr_b16 v[222:223], v160 offset:0x400
	ds_read_b64_tr_b16 v[224:225], v160 offset:0xc00
	s_waitcnt lgkmcnt(5)
	v_mfma_f32_32x32x16_bf16 v[16:31], v[226:229], v[176:179], v[16:31]
	s_waitcnt lgkmcnt(3)
	v_mfma_f32_32x32x16_bf16 v[16:31], v[230:233], v[180:183], v[16:31]
	ds_read_b64_tr_b16 v[226:227], v160 offset:0x1200
	ds_read_b64_tr_b16 v[228:229], v160 offset:0x1a00
	s_waitcnt lgkmcnt(4)
	v_mfma_f32_32x32x16_bf16 v[16:31], v[234:237], v[218:221], v[16:31]
	ds_read_b64_tr_b16 v[230:231], v160 offset:0x2200
	ds_read_b64_tr_b16 v[232:233], v160 offset:0x2a00
	ds_read_b64_tr_b16 v[234:235], v160 offset:0x3400
	ds_read_b64_tr_b16 v[236:237], v160 offset:0x3c00
	s_waitcnt lgkmcnt(6)
; DI void partialSM(f32x16& p0, f32x16& p1, float& m_reg, float& mn, float& alpha, const float SCALE) {
;   const float C = SCALE * 1.4426950408889634f;
;   float pmax = p0[0];
; template <int OFF> DI s16x4 tr_read(int vb) {
;   s16x4 r; asm volatile("ds_read_b64_tr_b16 %0, %1 offset:%2" : "=&v"(r) : "v"(vb), "i"(OFF) : "memory"); return r;
; }
; template <int D0, bool SPLIT> DI void pv_one(f32x16& od, int vb, bf16x8 pa0, bf16x8 pa1, bf16x8 pa2, bf16x8 pa3) {
;     ...
;   if constexpr (SPLIT) {
;     { const s16x4 l0 = tr_read<v_rd_off(D0, 0, 0)>(vb), h0 = tr_read<v_rd_off(D0, 0, 1)>(vb), l1 = tr_read<v_rd_off(D0, 1, 0)>(vb), h1 = tr_read<v_rd_off(D0, 1, 1)>(vb);
;       asm volatile("s_waitcnt lgkmcnt(0)" ::: "memory"); SBAR();
;       od = __builtin_amdgcn_mfma_f32_32x32x16_bf16(PKV(l0, h0), pa0, od, 0, 0, 0);
;       od = __builtin_amdgcn_mfma_f32_32x32x16_bf16(PKV(l1, h1), pa1, od, 0, 0, 0); }
;     SBAR();
;     { const s16x4 l2 = tr_read<v_rd_off(D0, 2, 0)>(vb), h2 = tr_read<v_rd_off(D0, 2, 1)>(vb), l3 = tr_read<v_rd_off(D0, 3, 0)>(vb), h3 = tr_read<v_rd_off(D0, 3, 1)>(vb);
;       asm volatile("s_waitcnt lgkmcnt(0)" ::: "memory"); SBAR();
;       od = __builtin_amdgcn_mfma_f32_32x32x16_bf16(PKV(l2, h2), pa2, od, 0, 0, 0);
;       od = __builtin_amdgcn_mfma_f32_32x32x16_bf16(PKV(l3, h3), pa3, od, 0, 0, 0); }
;     SBAR();
;   } else {
;   const s16x4 l0 = tr_read<v_rd_off(D0, 0, 0)>(vb), h0 = tr_read<v_rd_off(D0, 0, 1)>(vb), l1 = tr_read<v_rd_off(D0, 1, 0)>(vb), h1 = tr_read<v_rd_off(D0, 1, 1)>(vb);
;   const s16x4 l2 = tr_read<v_rd_off(D0, 2, 0)>(vb), h2 = tr_read<v_rd_off(D0, 2, 1)>(vb), l3 = tr_read<v_rd_off(D0, 3, 0)>(vb), h3 = tr_read<v_rd_off(D0, 3, 1)>(vb);
;   asm volatile("s_waitcnt lgkmcnt(0)" ::: "memory"); SBAR();
;   od = __builtin_amdgcn_mfma_f32_32x32x16_bf16(PKV(l0, h0), pa0, od, 0, 0, 0);
;   od = __builtin_amdgcn_mfma_f32_32x32x16_bf16(PKV(l1, h1), pa1, od, 0, 0, 0);
;   od = __builtin_amdgcn_mfma_f32_32x32x16_bf16(PKV(l2, h2), pa2, od, 0, 0, 0);
;   od = __builtin_amdgcn_mfma_f32_32x32x16_bf16(PKV(l3, h3), pa3, od, 0, 0, 0);
;   }
; }
; template <bool SPLIT>
; DI void pv_d0(f32x16* o, int vb, bf16x8 pa0, bf16x8 pa1, bf16x8 pa2, bf16x8 pa3) {
;   pv_one<0, SPLIT>(o[0], vb, pa0, pa1, pa2, pa3); pv_one<1, SPLIT>(o[1], vb, pa0, pa1, pa2, pa3); pv_one<2, SPLIT>(o[2], vb, pa0, pa1, pa2, pa3); pv_one<3, SPLIT>(o[3], vb, pa0, pa1, pa2, pa3);
; }
	v_mfma_f32_32x32x16_bf16 v[32:47], v[222:225], v[172:175], v[32:47]
	ds_read_b64_tr_b16 v[222:223], v160 offset:0x600
	ds_read_b64_tr_b16 v[224:225], v160 offset:0xe00
	s_waitcnt lgkmcnt(6)
	v_mfma_f32_32x32x16_bf16 v[48:63], v[226:229], v[176:179], v[48:63]
	s_waitcnt lgkmcnt(4)
	v_mfma_f32_32x32x16_bf16 v[48:63], v[230:233], v[180:183], v[48:63]
	ds_read_b64_tr_b16 v[226:227], v160 offset:0x1400
	ds_read_b64_tr_b16 v[228:229], v160 offset:0x1c00
	v_mfma_f32_32x32x16_bf16 v[48:63], v[238:241], v[218:221], v[48:63]
	ds_read_b64_tr_b16 v[230:231], v160 offset:0x2400
	ds_read_b64_tr_b16 v[232:233], v160 offset:0x2c00
	ds_read_b64_tr_b16 v[238:239], v160 offset:0x3600
	ds_read_b64_tr_b16 v[240:241], v160 offset:0x3e00
	s_waitcnt lgkmcnt(6)
	v_mfma_f32_32x32x16_bf16 v[0:15], v[222:225], v[172:175], v[0:15]
	s_waitcnt lgkmcnt(4)
	v_mfma_f32_32x32x16_bf16 v[32:47], v[226:229], v[176:179], v[32:47]
	s_waitcnt lgkmcnt(2)
	v_mfma_f32_32x32x16_bf16 v[32:47], v[230:233], v[180:183], v[32:47]
	ds_read_b64_tr_b16 v[226:227], v160 offset:0x1600
	ds_read_b64_tr_b16 v[228:229], v160 offset:0x1e00
	v_mfma_f32_32x32x16_bf16 v[32:47], v[234:237], v[218:221], v[32:47]
	ds_read_b64_tr_b16 v[230:231], v160 offset:0x2600
	ds_read_b64_tr_b16 v[232:233], v160 offset:0x2e00
	v_max_f32_e32 v160, v65, v65
	v_max_f32_e32 v160, v171, v160
	v_max3_f32 v160, v160, v66, v67
	v_max3_f32 v160, v160, v68, v69
	v_max3_f32 v160, v160, v70, v71
	v_max3_f32 v160, v160, v72, v73
	v_max3_f32 v160, v160, v74, v75
	v_max3_f32 v160, v160, v76, v77
	v_max3_f32 v160, v160, v78, v79
	v_max3_f32 v160, v160, v80, v81
	v_max3_f32 v160, v160, v82, v83
	v_max3_f32 v160, v160, v84, v85
	v_max3_f32 v160, v160, v86, v87
	v_max3_f32 v160, v160, v88, v89
	v_max3_f32 v160, v160, v90, v91
	v_max3_f32 v160, v160, v92, v93
	s_waitcnt lgkmcnt(2)
	v_mfma_f32_32x32x16_bf16 v[0:15], v[226:229], v[176:179], v[0:15]
	v_max3_f32 v160, v160, v94, v95
	v_mov_b32_e32 v171, v160
	s_waitcnt lgkmcnt(0)
	v_mfma_f32_32x32x16_bf16 v[0:15], v[230:233], v[180:183], v[0:15]
	v_mfma_f32_32x32x16_bf16 v[0:15], v[238:241], v[218:221], v[0:15]
	v_permlane32_swap_b32_e32 v160, v171
	v_max_f32_e32 v171, v171, v171
	v_max_f32_e32 v160, v160, v160
	v_max_f32_e32 v160, v160, v171
	v_max_f32_e32 v171, v170, v170
	v_sub_f32_e32 v172, v160, v170
	v_max_f32_e32 v171, v171, v160
	v_cmp_ge_f32_e32 vcc, s91, v172
	v_sub_f32_e32 v160, v170, v171
	v_mul_f32_e32 v160, 0x3dd53b94, v160
	s_cmp_eq_u64 vcc, exec
	v_exp_f32_e32 v160, v160
	s_cselect_b64 s[2:3], -1, 0
	v_cndmask_b32_e64 v160, v160, 1.0, s[2:3]
	v_cmp_gt_f32_e32 vcc, 1.0, v160
	s_cbranch_vccz .LBB0_932
	v_pk_mul_f32 v[30:31], v[30:31], v[160:161] op_sel_hi:[1,0]
	v_pk_mul_f32 v[28:29], v[28:29], v[160:161] op_sel_hi:[1,0]
	v_pk_mul_f32 v[26:27], v[26:27], v[160:161] op_sel_hi:[1,0]
	v_pk_mul_f32 v[24:25], v[24:25], v[160:161] op_sel_hi:[1,0]
	v_pk_mul_f32 v[22:23], v[22:23], v[160:161] op_sel_hi:[1,0]
	v_pk_mul_f32 v[20:21], v[20:21], v[160:161] op_sel_hi:[1,0]
	v_pk_mul_f32 v[18:19], v[18:19], v[160:161] op_sel_hi:[1,0]
	v_pk_mul_f32 v[16:17], v[16:17], v[160:161] op_sel_hi:[1,0]
	v_pk_mul_f32 v[62:63], v[62:63], v[160:161] op_sel_hi:[1,0]
	v_pk_mul_f32 v[60:61], v[60:61], v[160:161] op_sel_hi:[1,0]
	v_pk_mul_f32 v[58:59], v[58:59], v[160:161] op_sel_hi:[1,0]
	v_pk_mul_f32 v[56:57], v[56:57], v[160:161] op_sel_hi:[1,0]
	v_pk_mul_f32 v[54:55], v[54:55], v[160:161] op_sel_hi:[1,0]
	v_pk_mul_f32 v[52:53], v[52:53], v[160:161] op_sel_hi:[1,0]
	v_pk_mul_f32 v[50:51], v[50:51], v[160:161] op_sel_hi:[1,0]
	v_pk_mul_f32 v[48:49], v[48:49], v[160:161] op_sel_hi:[1,0]
	v_pk_mul_f32 v[46:47], v[46:47], v[160:161] op_sel_hi:[1,0]
	v_pk_mul_f32 v[44:45], v[44:45], v[160:161] op_sel_hi:[1,0]
	v_pk_mul_f32 v[42:43], v[42:43], v[160:161] op_sel_hi:[1,0]
	v_pk_mul_f32 v[40:41], v[40:41], v[160:161] op_sel_hi:[1,0]
	v_pk_mul_f32 v[38:39], v[38:39], v[160:161] op_sel_hi:[1,0]
	v_pk_mul_f32 v[36:37], v[36:37], v[160:161] op_sel_hi:[1,0]
	v_pk_mul_f32 v[34:35], v[34:35], v[160:161] op_sel_hi:[1,0]
	v_pk_mul_f32 v[32:33], v[32:33], v[160:161] op_sel_hi:[1,0]
	v_pk_mul_f32 v[14:15], v[14:15], v[160:161] op_sel_hi:[1,0]
	v_pk_mul_f32 v[12:13], v[12:13], v[160:161] op_sel_hi:[1,0]
	v_pk_mul_f32 v[10:11], v[10:11], v[160:161] op_sel_hi:[1,0]
	v_pk_mul_f32 v[8:9], v[8:9], v[160:161] op_sel_hi:[1,0]
	v_pk_mul_f32 v[6:7], v[6:7], v[160:161] op_sel_hi:[1,0]
	v_pk_mul_f32 v[4:5], v[4:5], v[160:161] op_sel_hi:[1,0]
	v_pk_mul_f32 v[2:3], v[2:3], v[160:161] op_sel_hi:[1,0]
	v_pk_mul_f32 v[0:1], v[0:1], v[160:161] op_sel_hi:[1,0]
